# v_rm_pool + two more exposed row loads of pool window variant 1 hoisted behind the previous batch
# baseline (speedup 1.0000x reference)
.LBB0_317:
	s_or_b32 s43, s18, 30
	s_or_b32 s38, s18, 31
	s_add_u32 s6, s43, s4
	s_addc_u32 s7, 0, s5
	s_add_i32 s8, s18, 45
	s_add_u32 s9, s38, s4
	s_addc_u32 s10, 0, s5
	s_add_i32 s11, s18, 46
	s_ashr_i32 s12, s11, 31
	s_cmp_gt_i32 s52, -1
	s_cselect_b32 s85, s10, s12
	s_cselect_b32 s84, s9, s11
	s_ashr_i32 s9, s8, 31
	s_cmp_gt_i32 s52, -1
	s_cselect_b32 s7, s7, s9
	s_cselect_b32 s6, s6, s8
	s_or_b32 s42, s18, 29
	s_add_u32 s8, s42, s4
	s_addc_u32 s9, 0, s5
	s_add_i32 s10, s18, 44
	s_ashr_i32 s11, s10, 31
	s_cmp_gt_i32 s52, -1
	s_cselect_b32 s9, s9, s11
	s_cselect_b32 s8, s8, s10
	s_or_b32 s46, s18, 28
	s_add_u32 s10, s46, s4
	s_addc_u32 s11, 0, s5
	s_add_i32 s12, s18, 43
	s_ashr_i32 s13, s12, 31
	s_cmp_gt_i32 s52, -1
	s_cselect_b32 s13, s11, s13
	s_cselect_b32 s12, s10, s12
	s_or_b32 s48, s18, 27
	s_add_u32 s10, s48, s4
	s_addc_u32 s11, 0, s5
	s_add_i32 s14, s18, 42
	s_ashr_i32 s15, s14, 31
	s_cmp_gt_i32 s52, -1
	s_cselect_b32 s15, s11, s15
	s_cselect_b32 s14, s10, s14
	s_or_b32 s50, s18, 26
	s_add_u32 s10, s50, s4
	s_addc_u32 s11, 0, s5
	s_add_i32 s16, s18, 41
	s_ashr_i32 s17, s16, 31
	s_cmp_gt_i32 s52, -1
	s_cselect_b32 s17, s11, s17
	s_cselect_b32 s16, s10, s16
	s_or_b32 s53, s18, 25
	s_add_u32 s10, s53, s4
	s_addc_u32 s11, 0, s5
	s_mov_b32 s86, s18
	s_add_i32 s18, s18, 40
	s_ashr_i32 s19, s18, 31
	s_cmp_gt_i32 s52, -1
	s_cselect_b32 s19, s11, s19
	s_cselect_b32 s18, s10, s18
	s_or_b32 s54, s86, 24
	s_add_u32 s10, s54, s4
	s_addc_u32 s11, 0, s5
	s_add_i32 s20, s86, 39
	s_ashr_i32 s21, s20, 31
	s_cmp_gt_i32 s52, -1
	s_cselect_b32 s21, s11, s21
	s_cselect_b32 s20, s10, s20
	s_or_b32 s66, s86, 23
	s_add_u32 s10, s66, s4
	s_addc_u32 s11, 0, s5
	s_add_i32 s22, s86, 38
	s_ashr_i32 s23, s22, 31
	s_cmp_gt_i32 s52, -1
	s_cselect_b32 s23, s11, s23
	s_cselect_b32 s22, s10, s22
	s_or_b32 s67, s86, 22
	s_add_u32 s10, s67, s4
	s_addc_u32 s11, 0, s5
	s_add_i32 s24, s86, 37
	s_ashr_i32 s25, s24, 31
	s_cmp_gt_i32 s52, -1
	s_cselect_b32 s25, s11, s25
	s_cselect_b32 s24, s10, s24
	s_or_b32 s72, s86, 21
	s_add_u32 s10, s72, s4
	s_addc_u32 s11, 0, s5
	s_add_i32 s26, s86, 36
	s_ashr_i32 s27, s26, 31
	s_cmp_gt_i32 s52, -1
	s_cselect_b32 s27, s11, s27
	s_cselect_b32 s26, s10, s26
	s_or_b32 s73, s86, 20
	s_add_u32 s10, s73, s4
	s_addc_u32 s11, 0, s5
	s_add_i32 s28, s86, 35
	s_ashr_i32 s29, s28, 31
	s_cmp_gt_i32 s52, -1
	s_cselect_b32 s29, s11, s29
	s_cselect_b32 s28, s10, s28
	s_or_b32 s74, s86, 19
	s_add_u32 s10, s74, s4
	s_addc_u32 s11, 0, s5
	s_add_i32 s30, s86, 34
	s_ashr_i32 s31, s30, 31
	s_cmp_gt_i32 s52, -1
	s_cselect_b32 s31, s11, s31
	s_cselect_b32 s30, s10, s30
	s_or_b32 s88, s86, 18
	s_add_u32 s10, s88, s4
	s_addc_u32 s11, 0, s5
	s_add_i32 s34, s86, 33
	s_ashr_i32 s35, s34, 31
	s_cmp_gt_i32 s52, -1
	s_cselect_b32 s35, s11, s35
	s_cselect_b32 s34, s10, s34
	s_or_b32 s89, s86, 17
	s_add_u32 s10, s89, s4
	s_addc_u32 s11, 0, s5
	s_add_i32 s36, s86, 32
	s_ashr_i32 s37, s36, 31
	s_cmp_gt_i32 s52, -1
	s_cselect_b32 s36, s10, s36
	s_cselect_b32 s37, s11, s37
	s_or_b32 vcc_lo, s86, 16
	s_add_u32 s10, vcc_lo, s4
	s_addc_u32 s11, 0, s5
	s_ashr_i32 s39, s38, 31
	v_writelane_b32 v254, s44, 57
	s_cmp_gt_i32 s52, -1
	v_writelane_b32 v254, s38, 48
	s_cselect_b32 s38, s10, s38
	s_cselect_b32 s39, s11, s39
	s_or_b32 s95, s86, 15
	s_add_u32 s10, s95, s4
	v_lshl_add_u64 v[76:77], s[40:41], 0, v[74:75]
	s_addc_u32 s11, 0, s5
	s_ashr_i32 s40, s43, 31
	s_cmp_gt_i32 s52, -1
	s_cselect_b32 s41, s11, s40
	s_cselect_b32 s40, s10, s43
	s_add_u32 s10, s44, s4
	s_addc_u32 s11, 0, s5
	s_mov_b32 s44, s42
	s_ashr_i32 s42, s42, 31
	v_writelane_b32 v254, s43, 49
	s_cmp_gt_i32 s52, -1
	v_writelane_b32 v254, s44, 50
	s_cselect_b32 s43, s11, s42
	s_cselect_b32 s42, s10, s44
	s_or_b32 s10, s86, 13
	v_writelane_b32 v254, s10, 59
	s_add_u32 s10, s10, s4
	s_addc_u32 s11, 0, s5
	s_ashr_i32 s44, s46, 31
	s_cmp_gt_i32 s52, -1
	v_writelane_b32 v254, s46, 52
	s_cselect_b32 s45, s11, s44
	s_cselect_b32 s44, s10, s46
	s_or_b32 s10, s86, 12
	v_writelane_b32 v254, s10, 61
	s_add_u32 s10, s10, s4
	s_addc_u32 s11, 0, s5
	s_ashr_i32 s46, s48, 31
	s_cmp_gt_i32 s52, -1
	v_writelane_b32 v254, s48, 54
	s_cselect_b32 s47, s11, s46
	s_cselect_b32 s46, s10, s48
	s_or_b32 s10, s86, 11
	v_writelane_b32 v254, s10, 63
	s_add_u32 s10, s10, s4
	s_addc_u32 s11, 0, s5
	s_ashr_i32 s48, s50, 31
	s_cmp_gt_i32 s52, -1
	s_cselect_b32 s49, s11, s48
	s_cselect_b32 s48, s10, s50
	s_or_b32 s10, s86, 10
	v_writelane_b32 v252, s10, 3
	s_add_u32 s10, s10, s4
	v_writelane_b32 v254, s50, 56
	s_addc_u32 s11, 0, s5
	s_ashr_i32 s50, s53, 31
	s_cmp_gt_i32 s52, -1
	s_cselect_b32 s51, s11, s50
	s_cselect_b32 s50, s10, s53
	s_or_b32 s10, s86, 9
	v_writelane_b32 v252, s10, 4
	s_add_u32 s10, s10, s4
	s_addc_u32 s11, 0, s5
	s_mov_b32 s94, s52
	s_ashr_i32 s52, s54, 31
	s_cmp_gt_i32 s94, -1
	v_writelane_b32 v254, s53, 58
	s_cselect_b32 s53, s11, s52
	s_cselect_b32 s52, s10, s54
	s_or_b32 s10, s86, 8
	v_writelane_b32 v252, s10, 5
	s_add_u32 s10, s10, s4
	v_writelane_b32 v254, s54, 60
	s_addc_u32 s11, 0, s5
	s_ashr_i32 s54, s66, 31
	s_cmp_gt_i32 s94, -1
	s_cselect_b32 s55, s11, s54
	s_cselect_b32 s54, s10, s66
	s_or_b32 s10, s86, 7
	v_writelane_b32 v252, s10, 9
	s_add_u32 s10, s10, s4
	v_writelane_b32 v254, s66, 62
	s_addc_u32 s11, 0, s5
	s_ashr_i32 s66, s67, 31
	s_cmp_gt_i32 s94, -1
	v_writelane_b32 v252, s67, 0
	s_cselect_b32 s81, s11, s66
	s_cselect_b32 s80, s10, s67
	s_or_b32 s10, s86, 6
	v_writelane_b32 v252, s10, 11
	s_add_u32 s10, s10, s4
	s_addc_u32 s11, 0, s5
	s_ashr_i32 s66, s72, 31
	s_cmp_gt_i32 s94, -1
	v_writelane_b32 v252, s72, 1
	s_cselect_b32 s79, s11, s66
	s_cselect_b32 s78, s10, s72
	s_or_b32 s10, s86, 5
	v_writelane_b32 v252, s10, 13
	s_add_u32 s10, s10, s4
	s_addc_u32 s11, 0, s5
	s_ashr_i32 s66, s73, 31
	s_cmp_gt_i32 s94, -1
	v_writelane_b32 v252, s73, 2
	s_cselect_b32 s91, s11, s66
	s_cselect_b32 s90, s10, s73
	s_or_b32 s10, s86, 4
	v_writelane_b32 v252, s10, 15
	s_add_u32 s10, s10, s4
	s_addc_u32 s11, 0, s5
	s_ashr_i32 s66, s74, 31
	s_cmp_gt_i32 s94, -1
	v_writelane_b32 v254, s74, 47
	s_cselect_b32 s75, s11, s66
	s_cselect_b32 s74, s10, s74
	s_or_b32 s10, s86, 3
	v_writelane_b32 v252, s10, 17
	s_add_u32 s10, s10, s4
	s_addc_u32 s11, 0, s5
	s_ashr_i32 s66, s88, 31
	s_cmp_gt_i32 s94, -1
	s_cselect_b32 s73, s11, s66
	s_cselect_b32 s72, s10, s88
	s_or_b32 s10, s86, 2
	v_writelane_b32 v252, s10, 18
	s_add_u32 s10, s10, s4
	s_addc_u32 s11, 0, s5
	s_ashr_i32 s66, s89, 31
	s_mov_b32 s67, s89
	s_cmp_gt_i32 s94, -1
	v_writelane_b32 v254, s88, 51
	s_cselect_b32 s89, s11, s66
	s_cselect_b32 s88, s10, s67
	s_or_b32 s10, s86, 1
	v_writelane_b32 v252, s10, 20
	s_add_u32 s10, s10, s4
	s_addc_u32 s11, 0, s5
	s_ashr_i32 s66, vcc_lo, 31
	s_cmp_gt_i32 s94, -1
	v_writelane_b32 v254, s67, 53
	s_cselect_b32 s11, s11, s66
	s_cselect_b32 s10, s10, vcc_lo
	v_writelane_b32 v252, s92, 7
	s_cselect_b32 s66, s96, s92
	s_cselect_b32 s67, s97, s93
	s_add_u32 s96, s86, s4
	v_writelane_b32 v254, vcc_lo, 55
	s_addc_u32 s97, 0, s5
	s_ashr_i32 vcc_lo, s95, 31
	s_cmp_gt_i32 s94, -1
	v_writelane_b32 v252, s93, 8
	s_cselect_b32 s97, s97, vcc_lo
	s_cselect_b32 s96, s96, s95
	s_lshl_b64 s[2:3], s[2:3], 11
	v_readlane_b32 s92, v254, 41
	s_cmp_lt_i32 s92, 1
	v_lshl_add_u64 v[134:135], v[76:77], 0, s[2:3]
	s_cselect_b64 vcc, -1, 0
	s_lshl_b64 s[2:3], s[96:97], 11
	v_lshl_add_u64 v[74:75], s[66:67], 0, v[74:75]
	s_cmp_lt_i32 s92, 0
	v_lshl_add_u64 v[136:137], v[74:75], 0, s[2:3]
	s_cselect_b64 s[66:67], -1, 0
	s_lshl_b64 s[2:3], s[10:11], 11
	s_cmp_lt_i32 s92, -1
	v_lshl_add_u64 v[138:139], v[74:75], 0, s[2:3]
	s_cselect_b64 s[2:3], -1, 0
	s_lshl_b64 s[10:11], s[88:89], 11
	s_cmp_lt_i32 s92, -2
	v_lshl_add_u64 v[140:141], v[74:75], 0, s[10:11]
	s_cselect_b64 s[88:89], -1, 0
	s_lshl_b64 s[10:11], s[72:73], 11
	s_cmp_lt_i32 s92, -3
	v_lshl_add_u64 v[142:143], v[74:75], 0, s[10:11]
	s_cselect_b64 s[72:73], -1, 0
	s_lshl_b64 s[10:11], s[74:75], 11
	s_cmp_lt_i32 s92, -4
	v_lshl_add_u64 v[144:145], v[74:75], 0, s[10:11]
	s_cselect_b64 s[74:75], -1, 0
	s_lshl_b64 s[10:11], s[90:91], 11
	s_cmp_lt_i32 s92, -5
	v_lshl_add_u64 v[146:147], v[74:75], 0, s[10:11]
	s_cselect_b64 s[90:91], -1, 0
	s_lshl_b64 s[10:11], s[78:79], 11
	s_cmp_lt_i32 s92, -6
	v_lshl_add_u64 v[148:149], v[74:75], 0, s[10:11]
	s_cselect_b64 s[78:79], -1, 0
	v_cndmask_b32_e64 v149, v149, v73, s[78:79]
	v_cndmask_b32_e64 v148, v148, v72, s[78:79]
	v_cndmask_b32_e64 v147, v147, v73, s[90:91]
	v_cndmask_b32_e64 v146, v146, v72, s[90:91]
	v_cndmask_b32_e64 v145, v145, v73, s[74:75]
	v_cndmask_b32_e64 v144, v144, v72, s[74:75]
	global_load_dwordx2 v[148:149], v[148:149], off
	v_cndmask_b32_e64 v143, v143, v73, s[72:73]
	global_load_dwordx2 v[146:147], v[146:147], off
	v_cndmask_b32_e64 v142, v142, v72, s[72:73]
	global_load_dwordx2 v[144:145], v[144:145], off
	v_cndmask_b32_e64 v141, v141, v73, s[88:89]
	v_cndmask_b32_e64 v140, v140, v72, s[88:89]
	v_cndmask_b32_e64 v139, v139, v73, s[2:3]
	v_cndmask_b32_e64 v138, v138, v72, s[2:3]
	v_cndmask_b32_e64 v137, v137, v73, s[66:67]
	v_cndmask_b32_e64 v136, v136, v72, s[66:67]
	v_cndmask_b32_e32 v135, v135, v73, vcc
	v_cndmask_b32_e32 v134, v134, v72, vcc
	s_lshl_b64 s[10:11], s[80:81], 11
	s_cmp_lt_i32 s92, -7
	v_lshl_add_u64 v[150:151], v[74:75], 0, s[10:11]
	s_cselect_b64 s[80:81], -1, 0
	s_lshl_b64 s[10:11], s[54:55], 11
	s_cmp_lt_i32 s92, -8
	v_lshl_add_u64 v[132:133], v[74:75], 0, s[10:11]
	s_cselect_b64 s[54:55], -1, 0
	s_lshl_b64 s[10:11], s[52:53], 11
	s_cmp_lt_i32 s92, -9
	v_lshl_add_u64 v[122:123], v[74:75], 0, s[10:11]
	s_cselect_b64 s[52:53], -1, 0
	s_lshl_b64 s[10:11], s[50:51], 11
	s_cmp_lt_i32 s92, -10
	v_lshl_add_u64 v[106:107], v[74:75], 0, s[10:11]
	s_cselect_b64 s[50:51], -1, 0
	s_lshl_b64 s[10:11], s[48:49], 11
	s_cmp_lt_i32 s92, -11
	v_lshl_add_u64 v[108:109], v[74:75], 0, s[10:11]
	s_cselect_b64 s[48:49], -1, 0
	s_lshl_b64 s[10:11], s[46:47], 11
	s_cmp_lt_i32 s92, -12
	v_lshl_add_u64 v[110:111], v[74:75], 0, s[10:11]
	s_cselect_b64 s[46:47], -1, 0
	s_lshl_b64 s[10:11], s[44:45], 11
	s_cmp_lt_i32 s92, -13
	v_lshl_add_u64 v[112:113], v[74:75], 0, s[10:11]
	s_cselect_b64 s[44:45], -1, 0
	s_lshl_b64 s[10:11], s[42:43], 11
	s_cmp_lt_i32 s92, -14
	v_lshl_add_u64 v[114:115], v[74:75], 0, s[10:11]
	s_cselect_b64 s[42:43], -1, 0
	s_lshl_b64 s[10:11], s[40:41], 11
	s_cmp_lt_i32 s92, -15
	v_lshl_add_u64 v[118:119], v[74:75], 0, s[10:11]
	s_cselect_b64 s[40:41], -1, 0
	s_lshl_b64 s[10:11], s[38:39], 11
	s_cmp_lt_i32 s92, -16
	v_lshl_add_u64 v[104:105], v[74:75], 0, s[10:11]
	s_cselect_b64 s[38:39], -1, 0
	s_lshl_b64 s[10:11], s[36:37], 11
	s_cmpk_lt_i32 s92, 0xffef
	v_lshl_add_u64 v[102:103], v[74:75], 0, s[10:11]
	s_cselect_b64 s[36:37], -1, 0
	s_lshl_b64 s[10:11], s[34:35], 11
	s_cmpk_lt_i32 s92, 0xffee
	v_lshl_add_u64 v[100:101], v[74:75], 0, s[10:11]
	s_cselect_b64 s[34:35], -1, 0
	s_lshl_b64 s[10:11], s[30:31], 11
	s_cmpk_lt_i32 s92, 0xffed
	v_lshl_add_u64 v[98:99], v[74:75], 0, s[10:11]
	s_cselect_b64 s[30:31], -1, 0
	s_lshl_b64 s[10:11], s[28:29], 11
	s_cmpk_lt_i32 s92, 0xffec
	v_lshl_add_u64 v[96:97], v[74:75], 0, s[10:11]
	s_cselect_b64 s[28:29], -1, 0
	s_lshl_b64 s[10:11], s[26:27], 11
	s_cmpk_lt_i32 s92, 0xffeb
	v_lshl_add_u64 v[94:95], v[74:75], 0, s[10:11]
	s_cselect_b64 s[26:27], -1, 0
	s_lshl_b64 s[10:11], s[24:25], 11
	s_cmpk_lt_i32 s92, 0xffea
	v_lshl_add_u64 v[92:93], v[74:75], 0, s[10:11]
	s_cselect_b64 s[24:25], -1, 0
	s_lshl_b64 s[10:11], s[22:23], 11
	s_cmpk_lt_i32 s92, 0xffe9
	v_lshl_add_u64 v[90:91], v[74:75], 0, s[10:11]
	s_waitcnt vmcnt(2)
	v_cndmask_b32_e64 v157, v149, 0, s[78:79]
	s_cselect_b64 s[22:23], -1, 0
	s_waitcnt vmcnt(1)
	v_cndmask_b32_e64 v159, v147, 0, s[90:91]
	s_lshl_b64 s[10:11], s[20:21], 11
	s_waitcnt vmcnt(0)
	v_cndmask_b32_e64 v149, v145, 0, s[74:75]
	v_cndmask_b32_e64 v147, v144, 0, s[74:75]
	global_load_dwordx2 v[144:145], v[142:143], off
	s_cmpk_lt_i32 s92, 0xffe8
	v_lshl_add_u64 v[88:89], v[74:75], 0, s[10:11]
	s_cselect_b64 s[20:21], -1, 0
	s_lshl_b64 s[10:11], s[18:19], 11
	s_cmpk_lt_i32 s92, 0xffe7
	v_lshl_add_u64 v[86:87], v[74:75], 0, s[10:11]
	s_cselect_b64 s[18:19], -1, 0
	s_lshl_b64 s[10:11], s[16:17], 11
	s_cmpk_lt_i32 s92, 0xffe6
	v_lshl_add_u64 v[84:85], v[74:75], 0, s[10:11]
	s_cselect_b64 s[16:17], -1, 0
	s_lshl_b64 s[10:11], s[14:15], 11
	s_cmpk_lt_i32 s92, 0xffe5
	v_lshl_add_u64 v[82:83], v[74:75], 0, s[10:11]
	s_cselect_b64 s[14:15], -1, 0
	s_lshl_b64 s[10:11], s[12:13], 11
	s_cmpk_lt_i32 s92, 0xffe4
	s_cselect_b64 s[12:13], -1, 0
	s_lshl_b64 s[8:9], s[8:9], 11
	s_cmpk_lt_i32 s92, 0xffe3
	v_lshl_add_u64 v[78:79], v[74:75], 0, s[8:9]
	s_cselect_b64 s[8:9], -1, 0
	s_lshl_b64 s[6:7], s[6:7], 11
	s_cmpk_lt_i32 s92, 0xffe2
	v_lshl_add_u64 v[80:81], v[74:75], 0, s[10:11]
	v_lshl_add_u64 v[76:77], v[74:75], 0, s[6:7]
	s_cselect_b64 s[6:7], -1, 0
	s_lshl_b64 s[10:11], s[84:85], 11
	s_cmpk_lt_i32 s92, 0xffe1
	v_lshl_add_u64 v[74:75], v[74:75], 0, s[10:11]
	s_cselect_b64 s[10:11], -1, 0
	v_cndmask_b32_e64 v166, v116, 0, s[82:83]
	v_cndmask_b32_e64 v165, v117, 0, s[82:83]
	v_cndmask_b32_e64 v158, v148, 0, s[78:79]
	v_cndmask_b32_e64 v148, v120, 0, s[56:57]
	v_cndmask_b32_e64 v161, v146, 0, s[90:91]
	v_cndmask_b32_e64 v146, v121, 0, s[56:57]
	v_cndmask_b32_e64 v151, v151, v73, s[80:81]
	v_cndmask_b32_e64 v150, v150, v72, s[80:81]
	global_load_dwordx2 v[150:151], v[150:151], off
	v_lshlrev_b32_e32 v184, 3, v153
	v_and_b32_e32 v179, 0x1f0, v184
	v_bitop3_b32 v175, v184, 16, v240 bitop3:0x6c
	v_bitop3_b32 v170, v184, 32, v240 bitop3:0x6c
	v_bitop3_b32 v167, v184, 48, v240 bitop3:0x6c
	v_bitop3_b32 v164, v184, 64, v240 bitop3:0x6c
	v_bitop3_b32 v155, v184, s33, v240 bitop3:0x6c
	v_cndmask_b32_e64 v107, v107, v73, s[50:51]
	v_cndmask_b32_e64 v106, v106, v72, s[50:51]
	v_cndmask_b32_e64 v125, v125, 0, s[58:59]
	v_cndmask_b32_e64 v124, v124, 0, s[58:59]
	v_lshlrev_b32_e32 v194, 16, v148
	v_and_b32_e32 v195, 0xffff0000, v148
	v_lshlrev_b32_e32 v196, 16, v146
	v_and_b32_e32 v197, 0xffff0000, v146
	v_cndmask_b32_e64 v127, v127, 0, s[60:61]
	v_cndmask_b32_e64 v126, v126, 0, s[60:61]
	v_cndmask_b32_e64 v129, v129, 0, s[62:63]
	v_cndmask_b32_e64 v128, v128, 0, s[62:63]
	v_lshlrev_b32_e32 v198, 16, v126
	v_and_b32_e32 v199, 0xffff0000, v126
	v_lshlrev_b32_e32 v126, 16, v127
	v_and_b32_e32 v127, 0xffff0000, v127
	v_cndmask_b32_e64 v131, v131, 0, s[64:65]
	v_cndmask_b32_e64 v130, v130, 0, s[64:65]
	v_lshlrev_b32_e32 v200, 16, v130
	v_and_b32_e32 v201, 0xffff0000, v130
	v_lshlrev_b32_e32 v130, 16, v131
	v_and_b32_e32 v131, 0xffff0000, v131
	v_lshlrev_b32_e32 v148, 16, v149
	v_and_b32_e32 v149, 0xffff0000, v149
	v_cndmask_b32_e64 v105, v105, v73, s[38:39]
	v_cndmask_b32_e64 v104, v104, v72, s[38:39]
	global_load_dwordx2 v[104:105], v[104:105], off
	v_cndmask_b32_e64 v103, v103, v73, s[36:37]
	v_cndmask_b32_e64 v102, v102, v72, s[36:37]
	global_load_dwordx2 v[102:103], v[102:103], off
	v_cndmask_b32_e64 v101, v101, v73, s[34:35]
	v_cndmask_b32_e64 v100, v100, v72, s[34:35]
	s_waitcnt vmcnt(3)
	v_cndmask_b32_e64 v142, v145, 0, s[72:73]
	v_cndmask_b32_e64 v143, v144, 0, s[72:73]
	global_load_dwordx2 v[144:145], v[140:141], off
	v_cndmask_b32_e64 v99, v99, v73, s[30:31]
	global_load_dwordx2 v[100:101], v[100:101], off
	v_cndmask_b32_e64 v98, v98, v72, s[30:31]
	global_load_dwordx2 v[98:99], v[98:99], off
	v_cndmask_b32_e64 v97, v97, v73, s[28:29]
	v_cndmask_b32_e64 v96, v96, v72, s[28:29]
	global_load_dwordx2 v[96:97], v[96:97], off
	v_cndmask_b32_e64 v95, v95, v73, s[26:27]
	v_cndmask_b32_e64 v94, v94, v72, s[26:27]
	global_load_dwordx2 v[94:95], v[94:95], off
	v_cndmask_b32_e64 v93, v93, v73, s[24:25]
	v_cndmask_b32_e64 v92, v92, v72, s[24:25]
	global_load_dwordx2 v[92:93], v[92:93], off
	v_cndmask_b32_e64 v91, v91, v73, s[22:23]
	v_cndmask_b32_e64 v90, v90, v72, s[22:23]
	global_load_dwordx2 v[90:91], v[90:91], off
	v_cndmask_b32_e64 v89, v89, v73, s[20:21]
	v_cndmask_b32_e64 v88, v88, v72, s[20:21]
	global_load_dwordx2 v[88:89], v[88:89], off
	v_cndmask_b32_e64 v87, v87, v73, s[18:19]
	v_cndmask_b32_e64 v86, v86, v72, s[18:19]
	global_load_dwordx2 v[86:87], v[86:87], off
	v_cndmask_b32_e64 v85, v85, v73, s[16:17]
	v_cndmask_b32_e64 v84, v84, v72, s[16:17]
	global_load_dwordx2 v[84:85], v[84:85], off
	v_cndmask_b32_e64 v83, v83, v73, s[14:15]
	v_cndmask_b32_e64 v82, v82, v72, s[14:15]
	global_load_dwordx2 v[82:83], v[82:83], off
	v_cndmask_b32_e64 v81, v81, v73, s[12:13]
	v_cndmask_b32_e64 v80, v80, v72, s[12:13]
	global_load_dwordx2 v[80:81], v[80:81], off
	v_cndmask_b32_e64 v77, v77, v73, s[6:7]
	v_cndmask_b32_e64 v76, v76, v72, s[6:7]
	global_load_dwordx2 v[76:77], v[76:77], off
	v_readlane_b32 s78, v254, 44
	v_readlane_b32 s96, v254, 39
	v_readlane_b32 s74, v254, 42
	s_waitcnt vmcnt(15)
	v_cndmask_b32_e64 v156, v150, 0, s[80:81]
	v_and_b32_e32 v150, 8, v184
	v_cndmask_b32_e64 v151, v151, 0, s[80:81]
	v_readlane_b32 s79, v254, 45
	v_readlane_b32 s97, v254, 40
	s_mov_b64 s[82:83], 0
	v_readlane_b32 s85, v254, 8
	v_readlane_b32 s93, v254, 10
	v_readlane_b32 s75, v254, 43
	v_readlane_b32 s80, v254, 15
	v_readlane_b32 s81, v254, 22
	v_readlane_b32 s84, v254, 23
	v_readlane_b32 s79, v254, 24
	s_mov_b32 s72, 0x40000
	s_waitcnt vmcnt(12)
	v_cndmask_b32_e64 v140, v145, 0, s[88:89]
	v_cndmask_b32_e64 v141, v144, 0, s[88:89]
	global_load_dwordx2 v[144:145], v[138:139], off
	global_load_dwordx2 v[188:189], v[136:137], off
	global_load_dwordx2 v[190:191], v[134:135], off
	v_readlane_b32 s89, v254, 14
	s_movk_i32 s88, 0x1000
	s_waitcnt vmcnt(10)
	v_cndmask_b32_e64 v93, v93, 0, s[24:25]
	s_waitcnt vmcnt(8)
	v_cndmask_b32_e64 v89, v89, 0, s[20:21]
	s_waitcnt vmcnt(7)
	v_cndmask_b32_e64 v87, v87, 0, s[18:19]
	s_waitcnt vmcnt(6)
	v_cndmask_b32_e64 v85, v85, 0, s[16:17]
	s_waitcnt vmcnt(5)
	v_cndmask_b32_e64 v83, v83, 0, s[14:15]
	s_waitcnt vmcnt(4)
	v_cndmask_b32_e64 v81, v81, 0, s[12:13]
	s_waitcnt vmcnt(3)
	v_cndmask_b32_e64 v77, v77, 0, s[6:7]
	s_waitcnt vmcnt(2)
	v_cndmask_b32_e64 v138, v145, 0, s[2:3]
	v_cndmask_b32_e64 v139, v144, 0, s[2:3]
	s_min_i32 s2, s92, 7
	s_add_i32 s2, s2, 1
	v_cvt_f32_i32_e32 v168, s2
	v_div_scale_f32 v71, s[2:3], v168, v168, 1.0
	v_rcp_f32_e32 v116, v71
	s_min_i32 s2, s92, 6
	s_add_i32 s2, s2, 2
	v_cvt_f32_i32_e32 v171, s2
	v_fma_f32 v117, -v71, v116, 1.0
	v_fmac_f32_e32 v116, v117, v116
	s_waitcnt vmcnt(1)
	v_cndmask_b32_e64 v136, v189, 0, s[66:67]
	v_cndmask_b32_e64 v137, v188, 0, s[66:67]
	v_lshlrev_b32_e32 v204, 16, v136
	v_and_b32_e32 v205, 0xffff0000, v136
	s_waitcnt vmcnt(0)
	v_cndmask_b32_e64 v134, v191, 0, vcc
	v_cndmask_b32_e64 v135, v190, 0, vcc
	v_cndmask_b32_e64 v189, v133, v73, s[54:55]
	v_cndmask_b32_e64 v188, v132, v72, s[54:55]
	global_load_dwordx2 v[188:189], v[188:189], off
	v_cndmask_b32_e64 v191, v123, v73, s[52:53]
	v_cndmask_b32_e64 v190, v122, v72, s[52:53]
	global_load_dwordx2 v[190:191], v[190:191], off
	v_div_scale_f32 v117, vcc, 1.0, v168, 1.0
	v_mul_f32_e32 v120, v117, v116
	v_fma_f32 v121, -v71, v120, v117
	v_fmac_f32_e32 v120, v121, v116
	v_fma_f32 v71, -v71, v120, v117
	v_div_fmas_f32 v169, v71, v116, v120
	v_div_scale_f32 v71, s[2:3], v171, v171, 1.0
	v_rcp_f32_e32 v116, v71
	s_min_i32 s2, s92, 5
	s_add_i32 s2, s2, 3
	v_cvt_f32_i32_e32 v173, s2
	v_fma_f32 v117, -v71, v116, 1.0
	v_fmac_f32_e32 v116, v117, v116
	v_div_scale_f32 v117, vcc, 1.0, v171, 1.0
	v_mul_f32_e32 v120, v117, v116
	v_fma_f32 v121, -v71, v120, v117
	v_fmac_f32_e32 v120, v121, v116
	v_fma_f32 v71, -v71, v120, v117
	v_div_fmas_f32 v172, v71, v116, v120
	v_div_scale_f32 v71, s[2:3], v173, v173, 1.0
	v_rcp_f32_e32 v116, v71
	s_min_i32 s2, s92, 4
	s_add_i32 s2, s2, 4
	v_cvt_f32_i32_e32 v176, s2
	v_fma_f32 v117, -v71, v116, 1.0
	v_fmac_f32_e32 v116, v117, v116
	v_div_scale_f32 v117, vcc, 1.0, v173, 1.0
	v_mul_f32_e32 v120, v117, v116
	v_fma_f32 v121, -v71, v120, v117
	v_fmac_f32_e32 v120, v121, v116
	v_fma_f32 v71, -v71, v120, v117
	v_div_fmas_f32 v174, v71, v116, v120
	v_div_scale_f32 v71, s[2:3], v176, v176, 1.0
	v_rcp_f32_e32 v116, v71
	s_min_i32 s2, s92, 3
	s_add_i32 s2, s2, 5
	v_cvt_f32_i32_e32 v178, s2
	v_fma_f32 v117, -v71, v116, 1.0
	v_fmac_f32_e32 v116, v117, v116
	v_div_scale_f32 v117, vcc, 1.0, v176, 1.0
	v_mul_f32_e32 v120, v117, v116
	v_fma_f32 v121, -v71, v120, v117
	v_fmac_f32_e32 v120, v121, v116
	v_fma_f32 v71, -v71, v120, v117
	v_div_fmas_f32 v177, v71, v116, v120
	v_div_scale_f32 v71, s[2:3], v178, v178, 1.0
	v_rcp_f32_e32 v116, v71
	s_min_i32 s2, s92, 2
	s_add_i32 s2, s2, 6
	v_cvt_f32_i32_e32 v181, s2
	v_fma_f32 v117, -v71, v116, 1.0
	v_fmac_f32_e32 v116, v117, v116
	v_div_scale_f32 v117, vcc, 1.0, v178, 1.0
	v_mul_f32_e32 v120, v117, v116
	v_fma_f32 v121, -v71, v120, v117
	v_fmac_f32_e32 v120, v121, v116
	v_fma_f32 v71, -v71, v120, v117
	v_div_fmas_f32 v180, v71, v116, v120
	v_div_scale_f32 v71, s[2:3], v181, v181, 1.0
	v_rcp_f32_e32 v116, v71
	s_min_i32 s2, s92, 1
	s_add_i32 s2, s2, 7
	v_cvt_f32_i32_e32 v183, s2
	v_fma_f32 v117, -v71, v116, 1.0
	v_fmac_f32_e32 v116, v117, v116
	v_div_scale_f32 v117, vcc, 1.0, v181, 1.0
	v_mul_f32_e32 v120, v117, v116
	v_fma_f32 v121, -v71, v120, v117
	v_fmac_f32_e32 v120, v121, v116
	v_fma_f32 v71, -v71, v120, v117
	v_div_fmas_f32 v182, v71, v116, v120
	v_div_scale_f32 v71, s[2:3], v183, v183, 1.0
	v_rcp_f32_e32 v116, v71
	s_min_i32 s2, s92, 0
	s_or_b32 s2, s2, 8
	v_cvt_f32_i32_e32 v186, s2
	v_fma_f32 v117, -v71, v116, 1.0
	v_fmac_f32_e32 v116, v117, v116
	v_div_scale_f32 v117, vcc, 1.0, v183, 1.0
	v_mul_f32_e32 v120, v117, v116
	v_fma_f32 v121, -v71, v120, v117
	v_fmac_f32_e32 v120, v121, v116
	v_fma_f32 v71, -v71, v120, v117
	v_div_fmas_f32 v185, v71, v116, v120
	v_div_scale_f32 v71, s[2:3], v186, v186, 1.0
	v_rcp_f32_e32 v116, v71
	s_min_i32 s2, s92, -1
	s_add_i32 s2, s2, 9
	v_cvt_f32_i32_e32 v210, s2
	v_fma_f32 v117, -v71, v116, 1.0
	v_fmac_f32_e32 v116, v117, v116
	v_div_scale_f32 v117, vcc, 1.0, v186, 1.0
	v_mul_f32_e32 v120, v117, v116
	v_fma_f32 v121, -v71, v120, v117
	v_fmac_f32_e32 v120, v121, v116
	v_fma_f32 v71, -v71, v120, v117
	v_div_fmas_f32 v187, v71, v116, v120
	v_div_scale_f32 v71, s[2:3], v210, v210, 1.0
	s_min_i32 s2, s92, -2
	s_add_i32 s2, s2, 10
	v_cvt_f32_i32_e32 v214, s2
	global_load_dwordx2 v[144:145], v[106:107], off
	v_cndmask_b32_e64 v107, v109, v73, s[48:49]
	v_cndmask_b32_e64 v106, v108, v72, s[48:49]
	v_lshlrev_b32_e32 v202, 16, v134
	v_and_b32_e32 v203, 0xffff0000, v134
	s_waitcnt vmcnt(2)
	v_cndmask_b32_e64 v209, v188, 0, s[54:55]
	v_rcp_f32_e32 v116, v71
	v_cndmask_b32_e64 v208, v189, 0, s[54:55]
	v_fma_f32 v117, -v71, v116, 1.0
	v_fmac_f32_e32 v116, v117, v116
	v_div_scale_f32 v117, vcc, 1.0, v210, 1.0
	v_mul_f32_e32 v120, v117, v116
	v_fma_f32 v121, -v71, v120, v117
	v_fmac_f32_e32 v120, v121, v116
	v_fma_f32 v71, -v71, v120, v117
	v_div_fmas_f32 v211, v71, v116, v120
	v_div_scale_f32 v71, s[2:3], v214, v214, 1.0
	s_lshl_b32 s2, s94, 14
	s_add_i32 s2, s2, 0
	v_add3_u32 v216, s2, v179, v150
	v_readlane_b32 s2, v252, 20
	s_lshl_b32 s2, s2, 9
	s_add_i32 s2, s2, 0
	v_add3_u32 v217, s2, v175, v150
	v_readlane_b32 s2, v252, 18
	s_lshl_b32 s2, s2, 9
	s_add_i32 s2, s2, 0
	v_add3_u32 v218, s2, v170, v150
	v_readlane_b32 s2, v252, 17
	s_lshl_b32 s2, s2, 9
	s_add_i32 s2, s2, 0
	v_add3_u32 v219, s2, v167, v150
	v_readlane_b32 s2, v252, 15
	s_lshl_b32 s2, s2, 9
	s_add_i32 s2, s2, 0
	v_add3_u32 v220, s2, v164, v150
	v_readlane_b32 s2, v252, 13
	s_lshl_b32 s2, s2, 9
	s_movk_i32 s3, 0x50
	s_add_i32 s2, s2, 0
	v_bitop3_b32 v163, v184, s3, v240 bitop3:0x6c
	v_add3_u32 v221, s2, v163, v150
	v_readlane_b32 s2, v252, 11
	s_lshl_b32 s2, s2, 9
	s_movk_i32 s3, 0x60
	s_add_i32 s2, s2, 0
	v_bitop3_b32 v162, v184, s3, v240 bitop3:0x6c
	v_add3_u32 v222, s2, v162, v150
	v_readlane_b32 s2, v252, 9
	s_lshl_b32 s2, s2, 9
	s_movk_i32 s3, 0x70
	s_add_i32 s2, s2, 0
	v_bitop3_b32 v160, v184, s3, v240 bitop3:0x6c
	v_add3_u32 v223, s2, v160, v150
	v_readlane_b32 s2, v252, 5
	s_lshl_b32 s2, s2, 9
	s_add_i32 s2, s2, 0
	v_add3_u32 v224, s2, v155, v150
	v_readlane_b32 s2, v254, 38
	global_load_dwordx2 v[122:123], v[106:107], off
	v_cndmask_b32_e64 v107, v111, v73, s[46:47]
	v_cndmask_b32_e64 v106, v110, v72, s[46:47]
	s_movk_i32 s3, 0x90
	s_waitcnt vmcnt(1)
	v_cndmask_b32_e64 v213, v190, 0, s[52:53]
	v_rcp_f32_e32 v116, v71
	v_cndmask_b32_e64 v212, v191, 0, s[52:53]
	s_mov_b32 s52, s94
	v_readlane_b32 s94, v254, 11
	v_fma_f32 v117, -v71, v116, 1.0
	v_fmac_f32_e32 v116, v117, v116
	v_div_scale_f32 v117, vcc, 1.0, v214, 1.0
	v_mul_f32_e32 v120, v117, v116
	v_fma_f32 v121, -v71, v120, v117
	v_fmac_f32_e32 v120, v121, v116
	v_fma_f32 v71, -v71, v120, v117
	v_div_fmas_f32 v215, v71, v116, v120
	v_mov_b32_e32 v71, s2
	global_load_dwordx2 v[116:117], v[106:107], off
	v_cndmask_b32_e64 v107, v113, v73, s[44:45]
	v_cndmask_b32_e64 v106, v112, v72, s[44:45]
	ds_read_b128 v[110:113], v71 offset:32
	ds_read_b128 v[188:191], v71 offset:48
	global_load_dwordx2 v[120:121], v[106:107], off
	v_cndmask_b32_e64 v107, v115, v73, s[42:43]
	v_cndmask_b32_e64 v106, v114, v72, s[42:43]
	global_load_dwordx2 v[108:109], v[106:107], off
	v_cndmask_b32_e64 v107, v119, v73, s[40:41]
	v_cndmask_b32_e64 v106, v118, v72, s[40:41]
	v_lshlrev_b32_e32 v114, 16, v166
	v_and_b32_e32 v115, 0xffff0000, v166
	v_lshlrev_b32_e32 v118, 16, v165
	v_and_b32_e32 v119, 0xffff0000, v165
	s_waitcnt lgkmcnt(1)
	v_pk_fma_f32 v[132:133], v[110:111], v[118:119], 0 op_sel_hi:[0,1,0]
	v_pk_fma_f32 v[192:193], v[110:111], v[114:115], 0 op_sel_hi:[0,1,0]
	v_pk_fma_f32 v[192:193], v[110:111], v[194:195], v[192:193] op_sel:[1,0,0]
	v_pk_fma_f32 v[110:111], v[110:111], v[196:197], v[132:133] op_sel:[1,0,0]
	v_lshlrev_b32_e32 v132, 16, v124
	v_and_b32_e32 v133, 0xffff0000, v124
	v_lshlrev_b32_e32 v124, 16, v125
	v_and_b32_e32 v125, 0xffff0000, v125
	v_pk_fma_f32 v[110:111], v[112:113], v[124:125], v[110:111] op_sel_hi:[0,1,1]
	v_pk_fma_f32 v[192:193], v[112:113], v[132:133], v[192:193] op_sel_hi:[0,1,1]
	v_mov_b32_e32 v112, v113
	v_pk_fma_f32 v[192:193], v[112:113], v[198:199], v[192:193] op_sel_hi:[0,1,1]
	v_pk_fma_f32 v[110:111], v[112:113], v[126:127], v[110:111] op_sel_hi:[0,1,1]
	v_lshlrev_b32_e32 v112, 16, v128
	v_and_b32_e32 v113, 0xffff0000, v128
	v_lshlrev_b32_e32 v128, 16, v129
	v_and_b32_e32 v129, 0xffff0000, v129
	s_waitcnt lgkmcnt(0)
	v_pk_fma_f32 v[110:111], v[188:189], v[128:129], v[110:111] op_sel_hi:[0,1,1]
	v_pk_fma_f32 v[192:193], v[188:189], v[112:113], v[192:193] op_sel_hi:[0,1,1]
	v_pk_fma_f32 v[192:193], v[188:189], v[200:201], v[192:193] op_sel:[1,0,0]
	v_pk_fma_f32 v[110:111], v[188:189], v[130:131], v[110:111] op_sel:[1,0,0]
	v_lshlrev_b32_e32 v188, 16, v135
	v_and_b32_e32 v189, 0xffff0000, v135
	v_pk_fma_f32 v[110:111], v[190:191], v[202:203], v[110:111] op_sel_hi:[0,1,1]
	v_pk_fma_f32 v[134:135], v[190:191], v[188:189], v[192:193] op_sel_hi:[0,1,1]
	v_lshlrev_b32_e32 v192, 16, v137
	v_and_b32_e32 v193, 0xffff0000, v137
	v_mov_b32_e32 v136, v191
	v_pk_mul_f32 v[190:191], v[136:137], v[192:193] op_sel_hi:[0,1]
	v_pk_mul_f32 v[206:207], v[136:137], v[204:205] op_sel_hi:[0,1]
	v_pk_fma_f32 v[134:135], v[136:137], v[192:193], v[134:135] op_sel_hi:[0,1,1]
	v_pk_fma_f32 v[110:111], v[136:137], v[204:205], v[110:111] op_sel_hi:[0,1,1]
	v_div_fixup_f32 v136, v169, v168, 1.0
	v_pk_fma_f32 v[168:169], v[136:137], v[110:111], v[206:207] op_sel_hi:[0,1,1] neg_lo:[0,0,1] neg_hi:[0,0,1]
	v_pk_fma_f32 v[136:137], v[136:137], v[134:135], v[190:191] op_sel_hi:[0,1,1] neg_lo:[0,0,1] neg_hi:[0,0,1]
	v_cvt_pk_bf16_f32 v136, v136, v137
	v_cvt_pk_bf16_f32 v137, v168, v169
	ds_write_b64 v216, v[136:137]
	ds_read_b32 v136, v71 offset:32
	ds_read_b32 v146, v71 offset:64
	v_lshlrev_b32_e32 v168, 16, v138
	v_and_b32_e32 v169, 0xffff0000, v138
	v_div_fixup_f32 v138, v172, v171, 1.0
	s_waitcnt lgkmcnt(1)
	v_pk_fma_f32 v[110:111], v[136:137], v[118:119], v[110:111] op_sel_hi:[0,1,1] neg_lo:[1,0,0] neg_hi:[1,0,0]
	v_pk_fma_f32 v[114:115], v[136:137], v[114:115], v[134:135] op_sel_hi:[0,1,1] neg_lo:[1,0,0] neg_hi:[1,0,0]
	v_lshlrev_b32_e32 v118, 16, v139
	v_and_b32_e32 v119, 0xffff0000, v139
	s_waitcnt lgkmcnt(0)
	v_pk_mul_f32 v[134:135], v[146:147], v[118:119] op_sel_hi:[0,1]
	v_pk_fma_f32 v[114:115], v[146:147], v[118:119], v[114:115] op_sel_hi:[0,1,1]
	v_pk_mul_f32 v[136:137], v[146:147], v[168:169] op_sel_hi:[0,1]
	v_pk_fma_f32 v[110:111], v[146:147], v[168:169], v[110:111] op_sel_hi:[0,1,1]
	v_pk_fma_f32 v[134:135], v[138:139], v[114:115], v[134:135] op_sel_hi:[0,1,1] neg_lo:[0,0,1] neg_hi:[0,0,1]
	v_pk_fma_f32 v[136:137], v[138:139], v[110:111], v[136:137] op_sel_hi:[0,1,1] neg_lo:[0,0,1] neg_hi:[0,0,1]
	v_cvt_pk_bf16_f32 v134, v134, v135
	v_cvt_pk_bf16_f32 v135, v136, v137
	ds_write_b64 v217, v[134:135]
	ds_read_b32 v134, v71 offset:36
	ds_read_b32 v136, v71 offset:68
	v_lshlrev_b32_e32 v190, 16, v141
	v_and_b32_e32 v191, 0xffff0000, v141
	v_lshlrev_b32_e32 v172, 16, v143
	s_waitcnt lgkmcnt(1)
	v_pk_fma_f32 v[110:111], v[134:135], v[196:197], v[110:111] op_sel_hi:[0,1,1] neg_lo:[1,0,0] neg_hi:[1,0,0]
	v_pk_fma_f32 v[114:115], v[134:135], v[194:195], v[114:115] op_sel_hi:[0,1,1] neg_lo:[1,0,0] neg_hi:[1,0,0]
	v_lshlrev_b32_e32 v194, 16, v140
	v_and_b32_e32 v195, 0xffff0000, v140
	s_waitcnt lgkmcnt(0)
	v_pk_mul_f32 v[134:135], v[136:137], v[190:191] op_sel_hi:[0,1]
	v_pk_mul_f32 v[138:139], v[136:137], v[194:195] op_sel_hi:[0,1]
	v_pk_fma_f32 v[114:115], v[136:137], v[190:191], v[114:115] op_sel_hi:[0,1,1]
	v_pk_fma_f32 v[110:111], v[136:137], v[194:195], v[110:111] op_sel_hi:[0,1,1]
	v_div_fixup_f32 v136, v174, v173, 1.0
	v_pk_fma_f32 v[134:135], v[136:137], v[114:115], v[134:135] op_sel_hi:[0,1,1] neg_lo:[0,0,1] neg_hi:[0,0,1]
	v_pk_fma_f32 v[138:139], v[136:137], v[110:111], v[138:139] op_sel_hi:[0,1,1] neg_lo:[0,0,1] neg_hi:[0,0,1]
	v_cvt_pk_bf16_f32 v134, v134, v135
	v_cvt_pk_bf16_f32 v135, v138, v139
	ds_write_b64 v218, v[134:135]
	ds_read_b32 v134, v71 offset:40
	ds_read_b32 v136, v71 offset:72
	v_and_b32_e32 v173, 0xffff0000, v143
	v_lshlrev_b32_e32 v196, 16, v142
	v_and_b32_e32 v197, 0xffff0000, v142
	s_waitcnt lgkmcnt(1)
	v_pk_fma_f32 v[114:115], v[134:135], v[132:133], v[114:115] op_sel_hi:[0,1,1] neg_lo:[1,0,0] neg_hi:[1,0,0]
	v_pk_fma_f32 v[110:111], v[134:135], v[124:125], v[110:111] op_sel_hi:[0,1,1] neg_lo:[1,0,0] neg_hi:[1,0,0]
	s_waitcnt lgkmcnt(0)
	v_pk_mul_f32 v[124:125], v[136:137], v[172:173] op_sel_hi:[0,1]
	v_pk_fma_f32 v[114:115], v[136:137], v[172:173], v[114:115] op_sel_hi:[0,1,1]
	v_div_fixup_f32 v134, v177, v176, 1.0
	v_pk_mul_f32 v[132:133], v[136:137], v[196:197] op_sel_hi:[0,1]
	v_pk_fma_f32 v[110:111], v[136:137], v[196:197], v[110:111] op_sel_hi:[0,1,1]
	v_pk_fma_f32 v[124:125], v[134:135], v[114:115], v[124:125] op_sel_hi:[0,1,1] neg_lo:[0,0,1] neg_hi:[0,0,1]
	v_pk_fma_f32 v[132:133], v[134:135], v[110:111], v[132:133] op_sel_hi:[0,1,1] neg_lo:[0,0,1] neg_hi:[0,0,1]
	v_cvt_pk_bf16_f32 v124, v124, v125
	v_cvt_pk_bf16_f32 v125, v132, v133
	ds_write_b64 v219, v[124:125]
	ds_read_b32 v124, v71 offset:44
	ds_read_b32 v132, v71 offset:76
	v_lshlrev_b32_e32 v146, 16, v147
	v_and_b32_e32 v147, 0xffff0000, v147
	v_lshlrev_b32_e32 v142, 16, v159
	s_waitcnt lgkmcnt(1)
	v_pk_fma_f32 v[110:111], v[124:125], v[126:127], v[110:111] op_sel_hi:[0,1,1] neg_lo:[1,0,0] neg_hi:[1,0,0]
	v_pk_fma_f32 v[114:115], v[124:125], v[198:199], v[114:115] op_sel_hi:[0,1,1] neg_lo:[1,0,0] neg_hi:[1,0,0]
	s_waitcnt lgkmcnt(0)
	v_pk_mul_f32 v[124:125], v[132:133], v[146:147] op_sel_hi:[0,1]
	v_pk_mul_f32 v[126:127], v[132:133], v[148:149] op_sel_hi:[0,1]
	v_pk_fma_f32 v[114:115], v[132:133], v[146:147], v[114:115] op_sel_hi:[0,1,1]
	v_pk_fma_f32 v[110:111], v[132:133], v[148:149], v[110:111] op_sel_hi:[0,1,1]
	v_div_fixup_f32 v132, v180, v178, 1.0
	v_pk_fma_f32 v[124:125], v[132:133], v[114:115], v[124:125] op_sel_hi:[0,1,1] neg_lo:[0,0,1] neg_hi:[0,0,1]
	v_pk_fma_f32 v[126:127], v[132:133], v[110:111], v[126:127] op_sel_hi:[0,1,1] neg_lo:[0,0,1] neg_hi:[0,0,1]
	v_cvt_pk_bf16_f32 v124, v124, v125
	v_cvt_pk_bf16_f32 v125, v126, v127
	ds_write_b64 v220, v[124:125]
	ds_read_b32 v124, v71 offset:48
	ds_read_b32 v126, v71 offset:80
	v_and_b32_e32 v143, 0xffff0000, v159
	v_lshlrev_b32_e32 v140, 16, v157
	v_and_b32_e32 v141, 0xffff0000, v157
	s_waitcnt lgkmcnt(1)
	v_pk_fma_f32 v[110:111], v[124:125], v[128:129], v[110:111] op_sel_hi:[0,1,1] neg_lo:[1,0,0] neg_hi:[1,0,0]
	v_pk_fma_f32 v[112:113], v[124:125], v[112:113], v[114:115] op_sel_hi:[0,1,1] neg_lo:[1,0,0] neg_hi:[1,0,0]
	v_lshlrev_b32_e32 v124, 16, v161
	v_and_b32_e32 v125, 0xffff0000, v161
	s_waitcnt lgkmcnt(0)
	v_pk_mul_f32 v[114:115], v[126:127], v[124:125] op_sel_hi:[0,1]
	v_pk_mul_f32 v[128:129], v[126:127], v[142:143] op_sel_hi:[0,1]
	v_pk_fma_f32 v[112:113], v[126:127], v[124:125], v[112:113] op_sel_hi:[0,1,1]
	v_pk_fma_f32 v[110:111], v[126:127], v[142:143], v[110:111] op_sel_hi:[0,1,1]
	v_div_fixup_f32 v126, v182, v181, 1.0
	v_pk_fma_f32 v[114:115], v[126:127], v[112:113], v[114:115] op_sel_hi:[0,1,1] neg_lo:[0,0,1] neg_hi:[0,0,1]
	v_pk_fma_f32 v[128:129], v[126:127], v[110:111], v[128:129] op_sel_hi:[0,1,1] neg_lo:[0,0,1] neg_hi:[0,0,1]
	v_cvt_pk_bf16_f32 v114, v114, v115
	v_cvt_pk_bf16_f32 v115, v128, v129
	ds_write_b64 v221, v[114:115]
	ds_read_b32 v114, v71 offset:52
	ds_read_b32 v128, v71 offset:84
	v_lshlrev_b32_e32 v126, 16, v158
	v_and_b32_e32 v127, 0xffff0000, v158
	v_lshlrev_b32_e32 v138, 16, v151
	s_waitcnt lgkmcnt(1)
	v_pk_fma_f32 v[110:111], v[114:115], v[130:131], v[110:111] op_sel_hi:[0,1,1] neg_lo:[1,0,0] neg_hi:[1,0,0]
	v_pk_fma_f32 v[112:113], v[114:115], v[200:201], v[112:113] op_sel_hi:[0,1,1] neg_lo:[1,0,0] neg_hi:[1,0,0]
	s_waitcnt lgkmcnt(0)
	v_pk_mul_f32 v[114:115], v[128:129], v[126:127] op_sel_hi:[0,1]
	v_pk_mul_f32 v[130:131], v[128:129], v[140:141] op_sel_hi:[0,1]
	v_pk_fma_f32 v[112:113], v[128:129], v[126:127], v[112:113] op_sel_hi:[0,1,1]
	v_pk_fma_f32 v[110:111], v[128:129], v[140:141], v[110:111] op_sel_hi:[0,1,1]
	v_div_fixup_f32 v128, v185, v183, 1.0
	v_pk_fma_f32 v[114:115], v[128:129], v[112:113], v[114:115] op_sel_hi:[0,1,1] neg_lo:[0,0,1] neg_hi:[0,0,1]
	v_pk_fma_f32 v[130:131], v[128:129], v[110:111], v[130:131] op_sel_hi:[0,1,1] neg_lo:[0,0,1] neg_hi:[0,0,1]
	v_cvt_pk_bf16_f32 v114, v114, v115
	v_cvt_pk_bf16_f32 v115, v130, v131
	ds_write_b64 v222, v[114:115]
	ds_read_b32 v114, v71 offset:56
	ds_read_b32 v128, v71 offset:88
	v_lshlrev_b32_e32 v130, 16, v156
	v_and_b32_e32 v131, 0xffff0000, v156
	v_and_b32_e32 v139, 0xffff0000, v151
	s_waitcnt lgkmcnt(1)
	v_pk_fma_f32 v[110:111], v[114:115], v[202:203], v[110:111] op_sel_hi:[0,1,1] neg_lo:[1,0,0] neg_hi:[1,0,0]
	v_pk_fma_f32 v[112:113], v[114:115], v[188:189], v[112:113] op_sel_hi:[0,1,1] neg_lo:[1,0,0] neg_hi:[1,0,0]
	s_waitcnt lgkmcnt(0)
	v_pk_mul_f32 v[114:115], v[128:129], v[130:131] op_sel_hi:[0,1]
	v_pk_mul_f32 v[132:133], v[128:129], v[138:139] op_sel_hi:[0,1]
	v_pk_fma_f32 v[112:113], v[128:129], v[130:131], v[112:113] op_sel_hi:[0,1,1]
	v_pk_fma_f32 v[110:111], v[128:129], v[138:139], v[110:111] op_sel_hi:[0,1,1]
	v_div_fixup_f32 v128, v187, v186, 1.0
	v_pk_fma_f32 v[114:115], v[128:129], v[112:113], v[114:115] op_sel_hi:[0,1,1] neg_lo:[0,0,1] neg_hi:[0,0,1]
	v_pk_fma_f32 v[132:133], v[128:129], v[110:111], v[132:133] op_sel_hi:[0,1,1] neg_lo:[0,0,1] neg_hi:[0,0,1]
	v_cvt_pk_bf16_f32 v114, v114, v115
	v_cvt_pk_bf16_f32 v115, v132, v133
	ds_write_b64 v223, v[114:115]
	ds_read_b32 v114, v71 offset:60
	ds_read_b32 v128, v71 offset:92
	v_lshlrev_b32_e32 v134, 16, v209
	v_and_b32_e32 v135, 0xffff0000, v209
	v_lshlrev_b32_e32 v136, 16, v208
	s_waitcnt lgkmcnt(1)
	v_pk_fma_f32 v[110:111], v[114:115], v[204:205], v[110:111] op_sel_hi:[0,1,1] neg_lo:[1,0,0] neg_hi:[1,0,0]
	v_pk_fma_f32 v[112:113], v[114:115], v[192:193], v[112:113] op_sel_hi:[0,1,1] neg_lo:[1,0,0] neg_hi:[1,0,0]
	v_and_b32_e32 v137, 0xffff0000, v208
	s_waitcnt lgkmcnt(0)
	v_pk_mul_f32 v[114:115], v[128:129], v[134:135] op_sel_hi:[0,1]
	v_pk_mul_f32 v[132:133], v[128:129], v[136:137] op_sel_hi:[0,1]
	v_pk_fma_f32 v[112:113], v[128:129], v[134:135], v[112:113] op_sel_hi:[0,1,1]
	v_pk_fma_f32 v[110:111], v[128:129], v[136:137], v[110:111] op_sel_hi:[0,1,1]
	v_div_fixup_f32 v128, v211, v210, 1.0
	v_pk_fma_f32 v[114:115], v[128:129], v[112:113], v[114:115] op_sel_hi:[0,1,1] neg_lo:[0,0,1] neg_hi:[0,0,1]
	v_pk_fma_f32 v[132:133], v[128:129], v[110:111], v[132:133] op_sel_hi:[0,1,1] neg_lo:[0,0,1] neg_hi:[0,0,1]
	v_cvt_pk_bf16_f32 v114, v114, v115
	v_cvt_pk_bf16_f32 v115, v132, v133
	ds_write_b64 v224, v[114:115]
	ds_read_b32 v114, v71 offset:64
	ds_read_b32 v156, v71 offset:96
	v_lshlrev_b32_e32 v128, 16, v213
	v_and_b32_e32 v129, 0xffff0000, v213
	v_lshlrev_b32_e32 v132, 16, v212
	s_waitcnt lgkmcnt(1)
	v_pk_fma_f32 v[110:111], v[114:115], v[168:169], v[110:111] op_sel_hi:[0,1,1] neg_lo:[1,0,0] neg_hi:[1,0,0]
	v_pk_fma_f32 v[112:113], v[114:115], v[118:119], v[112:113] op_sel_hi:[0,1,1] neg_lo:[1,0,0] neg_hi:[1,0,0]
	v_and_b32_e32 v133, 0xffff0000, v212
	v_readlane_b32 s2, v252, 4
	s_waitcnt lgkmcnt(0)
	v_pk_mul_f32 v[114:115], v[156:157], v[128:129] op_sel_hi:[0,1]
	v_pk_mul_f32 v[118:119], v[156:157], v[132:133] op_sel_hi:[0,1]
	v_pk_fma_f32 v[112:113], v[156:157], v[128:129], v[112:113] op_sel_hi:[0,1,1]
	v_pk_fma_f32 v[110:111], v[156:157], v[132:133], v[110:111] op_sel_hi:[0,1,1]
	v_div_fixup_f32 v156, v215, v214, 1.0
	s_lshl_b32 s2, s2, 9
	v_pk_fma_f32 v[118:119], v[156:157], v[110:111], v[118:119] op_sel_hi:[0,1,1] neg_lo:[0,0,1] neg_hi:[0,0,1]
	v_pk_fma_f32 v[114:115], v[156:157], v[112:113], v[114:115] op_sel_hi:[0,1,1] neg_lo:[0,0,1] neg_hi:[0,0,1]
	s_add_i32 s2, s2, 0
	v_bitop3_b32 v151, v184, s3, v240 bitop3:0x6c
	v_cvt_pk_bf16_f32 v114, v114, v115
	v_cvt_pk_bf16_f32 v115, v118, v119
	v_add3_u32 v118, s2, v151, v150
	s_min_i32 s2, s92, -3
	s_add_i32 s2, s2, 11
	v_cvt_f32_i32_e32 v161, s2
	ds_write_b64 v118, v[114:115]
	ds_read_b32 v114, v71 offset:68
	ds_read_b32 v118, v71 offset:100
	v_div_scale_f32 v165, s[2:3], v161, v161, 1.0
	v_rcp_f32_e32 v166, v165
	v_cndmask_b32_e64 v115, v145, 0, s[50:51]
	v_cndmask_b32_e64 v119, v144, 0, s[50:51]
	s_waitcnt lgkmcnt(1)
	v_pk_fma_f32 v[144:145], v[114:115], v[194:195], v[110:111] op_sel_hi:[0,1,1] neg_lo:[1,0,0] neg_hi:[1,0,0]
	v_pk_fma_f32 v[112:113], v[114:115], v[190:191], v[112:113] op_sel_hi:[0,1,1] neg_lo:[1,0,0] neg_hi:[1,0,0]
	v_lshlrev_b32_e32 v110, 16, v119
	v_and_b32_e32 v111, 0xffff0000, v119
	v_lshlrev_b32_e32 v114, 16, v115
	v_and_b32_e32 v115, 0xffff0000, v115
	s_waitcnt lgkmcnt(0)
	v_pk_mul_f32 v[156:157], v[118:119], v[110:111] op_sel_hi:[0,1]
	v_pk_mul_f32 v[158:159], v[118:119], v[114:115] op_sel_hi:[0,1]
	v_pk_fma_f32 v[112:113], v[118:119], v[110:111], v[112:113] op_sel_hi:[0,1,1]
	v_pk_fma_f32 v[118:119], v[118:119], v[114:115], v[144:145] op_sel_hi:[0,1,1]
	v_fma_f32 v144, -v165, v166, 1.0
	v_fmac_f32_e32 v166, v144, v166
	v_div_scale_f32 v144, vcc, 1.0, v161, 1.0
	v_mul_f32_e32 v145, v144, v166
	v_fma_f32 v168, -v165, v145, v144
	v_fmac_f32_e32 v145, v168, v166
	v_fma_f32 v144, -v165, v145, v144
	v_div_fmas_f32 v144, v144, v166, v145
	v_div_fixup_f32 v144, v144, v161, 1.0
	v_readlane_b32 s2, v252, 3
	v_pk_fma_f32 v[158:159], v[144:145], v[118:119], v[158:159] op_sel_hi:[0,1,1] neg_lo:[0,0,1] neg_hi:[0,0,1]
	v_pk_fma_f32 v[144:145], v[144:145], v[112:113], v[156:157] op_sel_hi:[0,1,1] neg_lo:[0,0,1] neg_hi:[0,0,1]
	s_lshl_b32 s2, s2, 9
	s_movk_i32 s3, 0xa0
	v_cvt_pk_bf16_f32 v156, v144, v145
	s_add_i32 s2, s2, 0
	v_bitop3_b32 v144, v184, s3, v240 bitop3:0x6c
	v_add3_u32 v145, s2, v144, v150
	v_cvt_pk_bf16_f32 v157, v158, v159
	ds_write_b64 v145, v[156:157]
	ds_read_b32 v156, v71 offset:72
	s_min_i32 s2, s92, -4
	s_waitcnt vmcnt(3)
	v_cndmask_b32_e64 v145, v122, 0, s[48:49]
	s_add_i32 s2, s2, 12
	ds_read_b32 v122, v71 offset:104
	s_waitcnt lgkmcnt(1)
	v_pk_fma_f32 v[158:159], v[156:157], v[196:197], v[118:119] op_sel_hi:[0,1,1] neg_lo:[1,0,0] neg_hi:[1,0,0]
	v_pk_fma_f32 v[156:157], v[156:157], v[172:173], v[112:113] op_sel_hi:[0,1,1] neg_lo:[1,0,0] neg_hi:[1,0,0]
	v_lshlrev_b32_e32 v112, 16, v145
	v_and_b32_e32 v113, 0xffff0000, v145
	v_cvt_f32_i32_e32 v145, s2
	v_cndmask_b32_e64 v123, v123, 0, s[48:49]
	global_load_dwordx2 v[106:107], v[106:107], off
	v_lshlrev_b32_e32 v118, 16, v123
	v_div_scale_f32 v161, s[2:3], v145, v145, 1.0
	v_rcp_f32_e32 v165, v161
	v_and_b32_e32 v119, 0xffff0000, v123
	s_waitcnt lgkmcnt(0)
	v_pk_mul_f32 v[168:169], v[122:123], v[112:113] op_sel_hi:[0,1]
	v_pk_mul_f32 v[172:173], v[122:123], v[118:119] op_sel_hi:[0,1]
	v_pk_fma_f32 v[156:157], v[122:123], v[112:113], v[156:157] op_sel_hi:[0,1,1]
	v_pk_fma_f32 v[122:123], v[122:123], v[118:119], v[158:159] op_sel_hi:[0,1,1]
	v_fma_f32 v158, -v161, v165, 1.0
	v_fmac_f32_e32 v165, v158, v165
	v_div_scale_f32 v158, vcc, 1.0, v145, 1.0
	v_mul_f32_e32 v159, v158, v165
	v_fma_f32 v166, -v161, v159, v158
	v_fmac_f32_e32 v159, v166, v165
	v_fma_f32 v158, -v161, v159, v158
	v_readlane_b32 s2, v254, 63
	v_div_fmas_f32 v158, v158, v165, v159
	s_lshl_b32 s2, s2, 9
	s_movk_i32 s3, 0xb0
	v_div_fixup_f32 v158, v158, v145, 1.0
	s_add_i32 s2, s2, 0
	v_bitop3_b32 v145, v184, s3, v240 bitop3:0x6c
	v_add3_u32 v161, s2, v145, v150
	s_min_i32 s2, s92, -5
	v_pk_fma_f32 v[172:173], v[158:159], v[122:123], v[172:173] op_sel_hi:[0,1,1] neg_lo:[0,0,1] neg_hi:[0,0,1]
	v_pk_fma_f32 v[158:159], v[158:159], v[156:157], v[168:169] op_sel_hi:[0,1,1] neg_lo:[0,0,1] neg_hi:[0,0,1]
	s_add_i32 s2, s2, 13
	v_cvt_pk_bf16_f32 v158, v158, v159
	v_cvt_pk_bf16_f32 v159, v172, v173
	ds_write_b64 v161, v[158:159]
	v_cvt_f32_i32_e32 v161, s2
	ds_read_b32 v158, v71 offset:76
	ds_read_b32 v166, v71 offset:108
	s_waitcnt vmcnt(3)
	v_cndmask_b32_e64 v159, v117, 0, s[46:47]
	v_div_scale_f32 v165, s[2:3], v161, v161, 1.0
	v_rcp_f32_e32 v171, v165
	v_cndmask_b32_e64 v117, v116, 0, s[46:47]
	s_waitcnt lgkmcnt(1)
	v_pk_fma_f32 v[146:147], v[158:159], v[146:147], v[156:157] op_sel_hi:[0,1,1] neg_lo:[1,0,0] neg_hi:[1,0,0]
	v_lshlrev_b32_e32 v116, 16, v117
	v_and_b32_e32 v117, 0xffff0000, v117
	s_waitcnt lgkmcnt(0)
	v_pk_fma_f32 v[168:169], v[166:167], v[116:117], v[146:147] op_sel_hi:[0,1,1]
	v_fma_f32 v146, -v165, v171, 1.0
	v_fmac_f32_e32 v171, v146, v171
	v_div_scale_f32 v146, vcc, 1.0, v161, 1.0
	v_pk_fma_f32 v[148:149], v[158:159], v[148:149], v[122:123] op_sel_hi:[0,1,1] neg_lo:[1,0,0] neg_hi:[1,0,0]
	v_lshlrev_b32_e32 v122, 16, v159
	v_and_b32_e32 v123, 0xffff0000, v159
	v_mul_f32_e32 v147, v146, v171
	v_pk_mul_f32 v[156:157], v[166:167], v[116:117] op_sel_hi:[0,1]
	v_pk_mul_f32 v[158:159], v[166:167], v[122:123] op_sel_hi:[0,1]
	v_pk_fma_f32 v[148:149], v[166:167], v[122:123], v[148:149] op_sel_hi:[0,1,1]
	v_fma_f32 v166, -v165, v147, v146
	v_fmac_f32_e32 v147, v166, v171
	v_fma_f32 v146, -v165, v147, v146
	v_div_fmas_f32 v146, v146, v171, v147
	v_div_fixup_f32 v146, v146, v161, 1.0
	v_readlane_b32 s2, v254, 61
	v_pk_fma_f32 v[158:159], v[146:147], v[148:149], v[158:159] op_sel_hi:[0,1,1] neg_lo:[0,0,1] neg_hi:[0,0,1]
	v_pk_fma_f32 v[146:147], v[146:147], v[168:169], v[156:157] op_sel_hi:[0,1,1] neg_lo:[0,0,1] neg_hi:[0,0,1]
	s_lshl_b32 s2, s2, 9
	s_movk_i32 s3, 0xc0
	v_cvt_pk_bf16_f32 v156, v146, v147
	s_add_i32 s2, s2, 0
	v_bitop3_b32 v146, v184, s3, v240 bitop3:0x6c
	v_add3_u32 v147, s2, v146, v150
	v_cvt_pk_bf16_f32 v157, v158, v159
	ds_write_b64 v147, v[156:157]
	s_min_i32 s2, s92, -6
	ds_read_b32 v156, v71 offset:80
	ds_read_b32 v158, v71 offset:112
	s_add_i32 s2, s2, 14
	v_cvt_f32_i32_e32 v161, s2
	s_waitcnt vmcnt(2)
	v_cndmask_b32_e64 v147, v121, 0, s[44:45]
	s_waitcnt lgkmcnt(1)
	v_pk_fma_f32 v[142:143], v[156:157], v[142:143], v[148:149] op_sel_hi:[0,1,1] neg_lo:[1,0,0] neg_hi:[1,0,0]
	v_pk_fma_f32 v[148:149], v[156:157], v[124:125], v[168:169] op_sel_hi:[0,1,1] neg_lo:[1,0,0] neg_hi:[1,0,0]
	v_lshlrev_b32_e32 v124, 16, v147
	v_and_b32_e32 v125, 0xffff0000, v147
	v_div_scale_f32 v147, s[2:3], v161, v161, 1.0
	v_rcp_f32_e32 v165, v147
	v_cndmask_b32_e64 v121, v120, 0, s[44:45]
	v_lshlrev_b32_e32 v120, 16, v121
	v_and_b32_e32 v121, 0xffff0000, v121
	s_waitcnt lgkmcnt(0)
	v_pk_mul_f32 v[156:157], v[158:159], v[120:121] op_sel_hi:[0,1]
	v_pk_mul_f32 v[168:169], v[158:159], v[124:125] op_sel_hi:[0,1]
	v_pk_fma_f32 v[148:149], v[158:159], v[120:121], v[148:149] op_sel_hi:[0,1,1]
	v_pk_fma_f32 v[158:159], v[158:159], v[124:125], v[142:143] op_sel_hi:[0,1,1]
	v_fma_f32 v142, -v147, v165, 1.0
	v_fmac_f32_e32 v165, v142, v165
	v_div_scale_f32 v142, vcc, 1.0, v161, 1.0
	v_mul_f32_e32 v143, v142, v165
	v_fma_f32 v166, -v147, v143, v142
	v_fmac_f32_e32 v143, v166, v165
	v_fma_f32 v142, -v147, v143, v142
	v_div_fmas_f32 v142, v142, v165, v143
	v_div_fixup_f32 v142, v142, v161, 1.0
	v_readlane_b32 s2, v254, 59
	v_pk_fma_f32 v[168:169], v[142:143], v[158:159], v[168:169] op_sel_hi:[0,1,1] neg_lo:[0,0,1] neg_hi:[0,0,1]
	v_pk_fma_f32 v[142:143], v[142:143], v[148:149], v[156:157] op_sel_hi:[0,1,1] neg_lo:[0,0,1] neg_hi:[0,0,1]
	s_lshl_b32 s2, s2, 9
	v_cvt_pk_bf16_f32 v156, v142, v143
	s_add_i32 s2, s2, 0
	v_bitop3_b32 v142, v184, s70, v240 bitop3:0x6c
	v_add3_u32 v143, s2, v142, v150
	v_cvt_pk_bf16_f32 v157, v168, v169
	ds_write_b64 v143, v[156:157]
	s_min_i32 s2, s92, -7
	ds_read_b32 v156, v71 offset:84
	ds_read_b32 v166, v71 offset:116
	s_add_i32 s2, s2, 15
	v_cvt_f32_i32_e32 v147, s2
	s_waitcnt vmcnt(1)
	v_cndmask_b32_e64 v143, v109, 0, s[42:43]
	s_waitcnt lgkmcnt(1)
	v_pk_fma_f32 v[148:149], v[156:157], v[126:127], v[148:149] op_sel_hi:[0,1,1] neg_lo:[1,0,0] neg_hi:[1,0,0]
	v_lshlrev_b32_e32 v126, 16, v143
	v_and_b32_e32 v127, 0xffff0000, v143
	v_div_scale_f32 v143, s[2:3], v147, v147, 1.0
	v_rcp_f32_e32 v161, v143
	v_pk_fma_f32 v[140:141], v[156:157], v[140:141], v[158:159] op_sel_hi:[0,1,1] neg_lo:[1,0,0] neg_hi:[1,0,0]
	s_waitcnt lgkmcnt(0)
	v_pk_fma_f32 v[168:169], v[166:167], v[126:127], v[140:141] op_sel_hi:[0,1,1]
	v_cndmask_b32_e64 v109, v108, 0, s[42:43]
	v_fma_f32 v140, -v143, v161, 1.0
	v_fmac_f32_e32 v161, v140, v161
	v_div_scale_f32 v140, vcc, 1.0, v147, 1.0
	v_mul_f32_e32 v141, v140, v161
	v_fma_f32 v165, -v143, v141, v140
	v_fmac_f32_e32 v141, v165, v161
	v_fma_f32 v140, -v143, v141, v140
	v_lshlrev_b32_e32 v108, 16, v109
	v_and_b32_e32 v109, 0xffff0000, v109
	v_div_fmas_f32 v140, v140, v161, v141
	v_pk_mul_f32 v[156:157], v[166:167], v[108:109] op_sel_hi:[0,1]
	v_pk_mul_f32 v[158:159], v[166:167], v[126:127] op_sel_hi:[0,1]
	v_pk_fma_f32 v[148:149], v[166:167], v[108:109], v[148:149] op_sel_hi:[0,1,1]
	v_div_fixup_f32 v140, v140, v147, 1.0
	v_readlane_b32 s2, v254, 57
	v_pk_fma_f32 v[158:159], v[140:141], v[168:169], v[158:159] op_sel_hi:[0,1,1] neg_lo:[0,0,1] neg_hi:[0,0,1]
	v_pk_fma_f32 v[140:141], v[140:141], v[148:149], v[156:157] op_sel_hi:[0,1,1] neg_lo:[0,0,1] neg_hi:[0,0,1]
	s_lshl_b32 s2, s2, 9
	v_cvt_pk_bf16_f32 v156, v140, v141
	s_add_i32 s2, s2, 0
	v_bitop3_b32 v140, v184, s71, v240 bitop3:0x6c
	v_add3_u32 v141, s2, v140, v150
	v_cvt_pk_bf16_f32 v157, v158, v159
	ds_write_b64 v141, v[156:157]
	s_min_i32 s2, s92, -8
	ds_read_b32 v156, v71 offset:88
	ds_read_b32 v158, v71 offset:120
	s_add_i32 s2, s2, 16
	v_cvt_f32_i32_e32 v143, s2
	s_waitcnt vmcnt(0)
	v_cndmask_b32_e64 v141, v107, 0, s[40:41]
	s_waitcnt lgkmcnt(1)
	v_pk_fma_f32 v[148:149], v[156:157], v[130:131], v[148:149] op_sel_hi:[0,1,1] neg_lo:[1,0,0] neg_hi:[1,0,0]
	v_lshlrev_b32_e32 v130, 16, v141
	v_and_b32_e32 v131, 0xffff0000, v141
	v_div_scale_f32 v141, s[2:3], v143, v143, 1.0
	v_rcp_f32_e32 v147, v141
	v_cndmask_b32_e64 v107, v106, 0, s[40:41]
	v_pk_fma_f32 v[138:139], v[156:157], v[138:139], v[168:169] op_sel_hi:[0,1,1] neg_lo:[1,0,0] neg_hi:[1,0,0]
	v_lshlrev_b32_e32 v106, 16, v107
	v_and_b32_e32 v107, 0xffff0000, v107
	s_waitcnt lgkmcnt(0)
	v_pk_mul_f32 v[156:157], v[158:159], v[106:107] op_sel_hi:[0,1]
	v_pk_mul_f32 v[168:169], v[158:159], v[130:131] op_sel_hi:[0,1]
	v_pk_fma_f32 v[148:149], v[158:159], v[106:107], v[148:149] op_sel_hi:[0,1,1]
	v_pk_fma_f32 v[158:159], v[158:159], v[130:131], v[138:139] op_sel_hi:[0,1,1]
	v_fma_f32 v138, -v141, v147, 1.0
	v_fmac_f32_e32 v147, v138, v147
	v_div_scale_f32 v138, vcc, 1.0, v143, 1.0
	v_mul_f32_e32 v139, v138, v147
	v_fma_f32 v161, -v141, v139, v138
	v_fmac_f32_e32 v139, v161, v147
	v_fma_f32 v138, -v141, v139, v138
	v_div_fmas_f32 v138, v138, v147, v139
	v_div_fixup_f32 v138, v138, v143, 1.0
	v_pk_fma_f32 v[168:169], v[138:139], v[158:159], v[168:169] op_sel_hi:[0,1,1] neg_lo:[0,0,1] neg_hi:[0,0,1]
	v_pk_fma_f32 v[138:139], v[138:139], v[148:149], v[156:157] op_sel_hi:[0,1,1] neg_lo:[0,0,1] neg_hi:[0,0,1]
	s_lshl_b32 s2, s95, 9
	v_cvt_pk_bf16_f32 v156, v138, v139
	s_add_i32 s2, s2, 0
	v_bitop3_b32 v138, v184, s76, v240 bitop3:0x6c
	v_add3_u32 v139, s2, v138, v150
	v_cvt_pk_bf16_f32 v157, v168, v169
	ds_write_b64 v139, v[156:157]
	s_min_i32 s2, s92, -9
	ds_read_b32 v156, v71 offset:92
	ds_read_b32 v166, v71 offset:124
	s_add_i32 s2, s2, 17
	v_cvt_f32_i32_e32 v141, s2
	v_cndmask_b32_e64 v139, v105, 0, s[38:39]
	s_waitcnt lgkmcnt(1)
	v_pk_fma_f32 v[148:149], v[156:157], v[134:135], v[148:149] op_sel_hi:[0,1,1] neg_lo:[1,0,0] neg_hi:[1,0,0]
	v_lshlrev_b32_e32 v134, 16, v139
	v_and_b32_e32 v135, 0xffff0000, v139
	v_div_scale_f32 v139, s[2:3], v141, v141, 1.0
	v_rcp_f32_e32 v143, v139
	v_cndmask_b32_e64 v105, v104, 0, s[38:39]
	v_readlane_b32 s2, v254, 55
	v_pk_fma_f32 v[136:137], v[156:157], v[136:137], v[158:159] op_sel_hi:[0,1,1] neg_lo:[1,0,0] neg_hi:[1,0,0]
	v_fma_f32 v147, -v139, v143, 1.0
	v_fmac_f32_e32 v143, v147, v143
	v_div_scale_f32 v147, vcc, 1.0, v141, 1.0
	v_mul_f32_e32 v161, v147, v143
	v_fma_f32 v165, -v139, v161, v147
	v_fmac_f32_e32 v161, v165, v143
	v_fma_f32 v139, -v139, v161, v147
	v_lshlrev_b32_e32 v104, 16, v105
	v_and_b32_e32 v105, 0xffff0000, v105
	v_div_fmas_f32 v139, v139, v143, v161
	s_lshl_b32 s2, s2, 9
	s_waitcnt lgkmcnt(0)
	v_pk_mul_f32 v[156:157], v[166:167], v[104:105] op_sel_hi:[0,1]
	v_pk_mul_f32 v[158:159], v[166:167], v[134:135] op_sel_hi:[0,1]
	v_pk_fma_f32 v[148:149], v[166:167], v[104:105], v[148:149] op_sel_hi:[0,1,1]
	v_pk_fma_f32 v[136:137], v[166:167], v[134:135], v[136:137] op_sel_hi:[0,1,1]
	v_div_fixup_f32 v166, v139, v141, 1.0
	s_add_i32 s2, s2, 0
	v_pk_fma_f32 v[156:157], v[166:167], v[148:149], v[156:157] op_sel_hi:[0,1,1] neg_lo:[0,0,1] neg_hi:[0,0,1]
	v_add3_u32 v139, s2, v179, v150
	v_pk_fma_f32 v[158:159], v[166:167], v[136:137], v[158:159] op_sel_hi:[0,1,1] neg_lo:[0,0,1] neg_hi:[0,0,1]
	v_cvt_pk_bf16_f32 v156, v156, v157
	v_cvt_pk_bf16_f32 v157, v158, v159
	ds_write_b64 v139, v[156:157]
	s_min_i32 s2, s92, -10
	ds_read_b32 v156, v71 offset:96
	ds_read_b32 v158, v71 offset:128
	s_add_i32 s2, s2, 18
	v_cvt_f32_i32_e32 v141, s2
	v_cndmask_b32_e64 v139, v103, 0, s[36:37]
	s_waitcnt lgkmcnt(1)
	v_pk_fma_f32 v[136:137], v[156:157], v[132:133], v[136:137] op_sel_hi:[0,1,1] neg_lo:[1,0,0] neg_hi:[1,0,0]
	v_lshlrev_b32_e32 v132, 16, v139
	v_and_b32_e32 v133, 0xffff0000, v139
	v_div_scale_f32 v139, s[2:3], v141, v141, 1.0
	v_rcp_f32_e32 v143, v139
	v_cndmask_b32_e64 v103, v102, 0, s[36:37]
	v_pk_fma_f32 v[128:129], v[156:157], v[128:129], v[148:149] op_sel_hi:[0,1,1] neg_lo:[1,0,0] neg_hi:[1,0,0]
	v_lshlrev_b32_e32 v102, 16, v103
	v_fma_f32 v147, -v139, v143, 1.0
	v_and_b32_e32 v103, 0xffff0000, v103
	v_fmac_f32_e32 v143, v147, v143
	v_div_scale_f32 v147, vcc, 1.0, v141, 1.0
	s_waitcnt lgkmcnt(0)
	v_pk_mul_f32 v[148:149], v[158:159], v[102:103] op_sel_hi:[0,1]
	v_pk_mul_f32 v[156:157], v[158:159], v[132:133] op_sel_hi:[0,1]
	v_pk_fma_f32 v[128:129], v[158:159], v[102:103], v[128:129] op_sel_hi:[0,1,1]
	v_pk_fma_f32 v[136:137], v[158:159], v[132:133], v[136:137] op_sel_hi:[0,1,1]
	v_mul_f32_e32 v158, v147, v143
	v_fma_f32 v159, -v139, v158, v147
	v_fmac_f32_e32 v158, v159, v143
	v_fma_f32 v139, -v139, v158, v147
	v_readlane_b32 s2, v254, 53
	v_div_fmas_f32 v139, v139, v143, v158
	s_lshl_b32 s2, s2, 9
	v_div_fixup_f32 v158, v139, v141, 1.0
	s_add_i32 s2, s2, 0
	v_pk_fma_f32 v[148:149], v[158:159], v[128:129], v[148:149] op_sel_hi:[0,1,1] neg_lo:[0,0,1] neg_hi:[0,0,1]
	v_add3_u32 v139, s2, v175, v150
	v_pk_fma_f32 v[156:157], v[158:159], v[136:137], v[156:157] op_sel_hi:[0,1,1] neg_lo:[0,0,1] neg_hi:[0,0,1]
	v_cvt_pk_bf16_f32 v148, v148, v149
	v_cvt_pk_bf16_f32 v149, v156, v157
	ds_write_b64 v139, v[148:149]
	s_min_i32 s2, s92, -11
	ds_read_b32 v148, v71 offset:100
	ds_read_b32 v156, v71 offset:132
	s_add_i32 s2, s2, 19
	v_cvt_f32_i32_e32 v141, s2
	v_cndmask_b32_e64 v139, v101, 0, s[34:35]
	s_waitcnt lgkmcnt(1)
	v_pk_fma_f32 v[110:111], v[148:149], v[110:111], v[128:129] op_sel_hi:[0,1,1] neg_lo:[1,0,0] neg_hi:[1,0,0]
	v_lshlrev_b32_e32 v128, 16, v139
	v_and_b32_e32 v129, 0xffff0000, v139
	v_div_scale_f32 v139, s[2:3], v141, v141, 1.0
	v_rcp_f32_e32 v143, v139
	v_cndmask_b32_e64 v101, v100, 0, s[34:35]
	v_pk_fma_f32 v[114:115], v[148:149], v[114:115], v[136:137] op_sel_hi:[0,1,1] neg_lo:[1,0,0] neg_hi:[1,0,0]
	v_lshlrev_b32_e32 v100, 16, v101
	v_fma_f32 v147, -v139, v143, 1.0
	v_and_b32_e32 v101, 0xffff0000, v101
	v_fmac_f32_e32 v143, v147, v143
	v_div_scale_f32 v147, vcc, 1.0, v141, 1.0
	s_waitcnt lgkmcnt(0)
	v_pk_mul_f32 v[136:137], v[156:157], v[100:101] op_sel_hi:[0,1]
	v_pk_mul_f32 v[148:149], v[156:157], v[128:129] op_sel_hi:[0,1]
	v_pk_fma_f32 v[110:111], v[156:157], v[100:101], v[110:111] op_sel_hi:[0,1,1]
	v_pk_fma_f32 v[114:115], v[156:157], v[128:129], v[114:115] op_sel_hi:[0,1,1]
	v_mul_f32_e32 v156, v147, v143
	v_fma_f32 v157, -v139, v156, v147
	v_fmac_f32_e32 v156, v157, v143
	v_readlane_b32 s2, v254, 51
	v_fma_f32 v139, -v139, v156, v147
	s_lshl_b32 s2, s2, 9
	v_div_fmas_f32 v139, v139, v143, v156
	s_add_i32 s2, s2, 0
	v_div_fixup_f32 v156, v139, v141, 1.0
	v_add3_u32 v139, s2, v170, v150
	s_min_i32 s2, s92, -12
	v_pk_fma_f32 v[136:137], v[156:157], v[110:111], v[136:137] op_sel_hi:[0,1,1] neg_lo:[0,0,1] neg_hi:[0,0,1]
	s_add_i32 s2, s2, 20
	v_pk_fma_f32 v[148:149], v[156:157], v[114:115], v[148:149] op_sel_hi:[0,1,1] neg_lo:[0,0,1] neg_hi:[0,0,1]
	v_cvt_pk_bf16_f32 v136, v136, v137
	v_cvt_pk_bf16_f32 v137, v148, v149
	ds_write_b64 v139, v[136:137]
	v_cvt_f32_i32_e32 v139, s2
	ds_read_b32 v136, v71 offset:104
	ds_read_b32 v148, v71 offset:136
	v_cndmask_b32_e64 v137, v99, 0, s[30:31]
	v_div_scale_f32 v141, s[2:3], v139, v139, 1.0
	v_rcp_f32_e32 v143, v141
	v_cndmask_b32_e64 v99, v98, 0, s[30:31]
	s_waitcnt lgkmcnt(1)
	v_pk_fma_f32 v[118:119], v[136:137], v[118:119], v[114:115] op_sel_hi:[0,1,1] neg_lo:[1,0,0] neg_hi:[1,0,0]
	v_pk_fma_f32 v[110:111], v[136:137], v[112:113], v[110:111] op_sel_hi:[0,1,1] neg_lo:[1,0,0] neg_hi:[1,0,0]
	v_fma_f32 v147, -v141, v143, 1.0
	v_lshlrev_b32_e32 v98, 16, v99
	v_and_b32_e32 v99, 0xffff0000, v99
	v_lshlrev_b32_e32 v114, 16, v137
	v_and_b32_e32 v115, 0xffff0000, v137
	v_fmac_f32_e32 v143, v147, v143
	v_div_scale_f32 v147, vcc, 1.0, v139, 1.0
	s_waitcnt lgkmcnt(0)
	v_pk_mul_f32 v[112:113], v[148:149], v[98:99] op_sel_hi:[0,1]
	v_pk_mul_f32 v[136:137], v[148:149], v[114:115] op_sel_hi:[0,1]
	v_pk_fma_f32 v[110:111], v[148:149], v[98:99], v[110:111] op_sel_hi:[0,1,1]
	v_pk_fma_f32 v[118:119], v[148:149], v[114:115], v[118:119] op_sel_hi:[0,1,1]
	v_mul_f32_e32 v148, v147, v143
	v_fma_f32 v149, -v141, v148, v147
	v_fmac_f32_e32 v148, v149, v143
	v_fma_f32 v141, -v141, v148, v147
	v_div_fmas_f32 v141, v141, v143, v148
	v_readlane_b32 s2, v254, 47
	v_div_fixup_f32 v148, v141, v139, 1.0
	s_lshl_b32 s2, s2, 9
	v_pk_fma_f32 v[136:137], v[148:149], v[118:119], v[136:137] op_sel_hi:[0,1,1] neg_lo:[0,0,1] neg_hi:[0,0,1]
	v_pk_fma_f32 v[112:113], v[148:149], v[110:111], v[112:113] op_sel_hi:[0,1,1] neg_lo:[0,0,1] neg_hi:[0,0,1]
	s_add_i32 s2, s2, 0
	v_cvt_pk_bf16_f32 v112, v112, v113
	v_cvt_pk_bf16_f32 v113, v136, v137
	v_add3_u32 v136, s2, v167, v150
	s_min_i32 s2, s92, -13
	s_add_i32 s2, s2, 21
	v_cvt_f32_i32_e32 v137, s2
	ds_write_b64 v136, v[112:113]
	ds_read_b32 v112, v71 offset:108
	ds_read_b32 v136, v71 offset:140
	v_div_scale_f32 v139, s[2:3], v137, v137, 1.0
	v_rcp_f32_e32 v141, v139
	v_cndmask_b32_e64 v113, v97, 0, s[28:29]
	v_cndmask_b32_e64 v97, v96, 0, s[28:29]
	s_waitcnt lgkmcnt(1)
	v_pk_fma_f32 v[118:119], v[112:113], v[122:123], v[118:119] op_sel_hi:[0,1,1] neg_lo:[1,0,0] neg_hi:[1,0,0]
	v_pk_fma_f32 v[110:111], v[112:113], v[116:117], v[110:111] op_sel_hi:[0,1,1] neg_lo:[1,0,0] neg_hi:[1,0,0]
	v_lshlrev_b32_e32 v96, 16, v97
	v_and_b32_e32 v97, 0xffff0000, v97
	v_lshlrev_b32_e32 v112, 16, v113
	v_and_b32_e32 v113, 0xffff0000, v113
	s_waitcnt lgkmcnt(0)
	v_pk_mul_f32 v[116:117], v[136:137], v[96:97] op_sel_hi:[0,1]
	v_pk_mul_f32 v[122:123], v[136:137], v[112:113] op_sel_hi:[0,1]
	v_pk_fma_f32 v[110:111], v[136:137], v[96:97], v[110:111] op_sel_hi:[0,1,1]
	v_pk_fma_f32 v[118:119], v[136:137], v[112:113], v[118:119] op_sel_hi:[0,1,1]
	v_fma_f32 v136, -v139, v141, 1.0
	v_fmac_f32_e32 v141, v136, v141
	v_div_scale_f32 v136, vcc, 1.0, v137, 1.0
	v_mul_f32_e32 v143, v136, v141
	v_fma_f32 v147, -v139, v143, v136
	v_fmac_f32_e32 v143, v147, v141
	v_fma_f32 v136, -v139, v143, v136
	v_div_fmas_f32 v136, v136, v141, v143
	v_readlane_b32 s2, v252, 2
	v_div_fixup_f32 v136, v136, v137, 1.0
	s_lshl_b32 s2, s2, 9
	v_pk_fma_f32 v[122:123], v[136:137], v[118:119], v[122:123] op_sel_hi:[0,1,1] neg_lo:[0,0,1] neg_hi:[0,0,1]
	v_pk_fma_f32 v[116:117], v[136:137], v[110:111], v[116:117] op_sel_hi:[0,1,1] neg_lo:[0,0,1] neg_hi:[0,0,1]
	s_add_i32 s2, s2, 0
	v_cvt_pk_bf16_f32 v116, v116, v117
	v_cvt_pk_bf16_f32 v117, v122, v123
	v_add3_u32 v122, s2, v164, v150
	ds_write_b64 v122, v[116:117]
	ds_read_b32 v116, v71 offset:112
	ds_read_b32 v122, v71 offset:144
	s_min_i32 s2, s92, -14
	v_cndmask_b32_e64 v117, v79, v73, s[8:9]
	s_add_i32 s2, s2, 22
	s_waitcnt lgkmcnt(1)
	v_pk_fma_f32 v[118:119], v[116:117], v[124:125], v[118:119] op_sel_hi:[0,1,1] neg_lo:[1,0,0] neg_hi:[1,0,0]
	v_pk_fma_f32 v[120:121], v[116:117], v[120:121], v[110:111] op_sel_hi:[0,1,1] neg_lo:[1,0,0] neg_hi:[1,0,0]
	v_cvt_f32_i32_e32 v116, s2
	v_cndmask_b32_e64 v79, v95, 0, s[26:27]
	v_cndmask_b32_e64 v95, v94, 0, s[26:27]
	v_lshlrev_b32_e32 v94, 16, v95
	v_and_b32_e32 v95, 0xffff0000, v95
	v_lshlrev_b32_e32 v110, 16, v79
	v_and_b32_e32 v111, 0xffff0000, v79
	v_div_scale_f32 v79, s[2:3], v116, v116, 1.0
	s_waitcnt lgkmcnt(0)
	v_pk_mul_f32 v[124:125], v[122:123], v[94:95] op_sel_hi:[0,1]
	v_rcp_f32_e32 v123, v79
	v_readlane_b32 s2, v252, 1
	s_lshl_b32 s2, s2, 9
	s_add_i32 s2, s2, 0
	v_pk_mul_f32 v[136:137], v[122:123], v[110:111] op_sel_hi:[0,1]
	v_pk_fma_f32 v[120:121], v[122:123], v[94:95], v[120:121] op_sel_hi:[0,1,1]
	v_pk_fma_f32 v[118:119], v[122:123], v[110:111], v[118:119] op_sel_hi:[0,1,1]
	v_fma_f32 v122, -v79, v123, 1.0
	v_fmac_f32_e32 v123, v122, v123
	v_div_scale_f32 v122, vcc, 1.0, v116, 1.0
	v_mul_f32_e32 v139, v122, v123
	v_fma_f32 v141, -v79, v139, v122
	v_fmac_f32_e32 v139, v141, v123
	v_fma_f32 v79, -v79, v139, v122
	v_div_fmas_f32 v79, v79, v123, v139
	v_div_fixup_f32 v116, v79, v116, 1.0
	v_pk_fma_f32 v[124:125], v[116:117], v[120:121], v[124:125] op_sel_hi:[0,1,1] neg_lo:[0,0,1] neg_hi:[0,0,1]
	v_add3_u32 v79, s2, v163, v150
	s_min_i32 s2, s92, -15
	v_pk_fma_f32 v[122:123], v[116:117], v[118:119], v[136:137] op_sel_hi:[0,1,1] neg_lo:[0,0,1] neg_hi:[0,0,1]
	v_cvt_pk_bf16_f32 v124, v124, v125
	v_cvt_pk_bf16_f32 v125, v122, v123
	s_add_i32 s2, s2, 23
	ds_write_b64 v79, v[124:125]
	v_cvt_f32_i32_e32 v125, s2
	ds_read_b32 v122, v71 offset:116
	ds_read_b32 v124, v71 offset:148
	v_cndmask_b32_e64 v79, v92, 0, s[24:25]
	v_div_scale_f32 v136, s[2:3], v125, v125, 1.0
	v_rcp_f32_e32 v137, v136
	v_cndmask_b32_e64 v116, v78, v72, s[8:9]
	s_waitcnt lgkmcnt(1)
	v_pk_fma_f32 v[108:109], v[122:123], v[108:109], v[120:121] op_sel_hi:[0,1,1] neg_lo:[1,0,0] neg_hi:[1,0,0]
	v_lshlrev_b32_e32 v78, 16, v79
	v_and_b32_e32 v79, 0xffff0000, v79
	v_pk_fma_f32 v[118:119], v[122:123], v[126:127], v[118:119] op_sel_hi:[0,1,1] neg_lo:[1,0,0] neg_hi:[1,0,0]
	s_waitcnt lgkmcnt(0)
	v_pk_fma_f32 v[126:127], v[124:125], v[78:79], v[108:109] op_sel_hi:[0,1,1]
	v_fma_f32 v108, -v136, v137, 1.0
	v_fmac_f32_e32 v137, v108, v137
	v_div_scale_f32 v108, vcc, 1.0, v125, 1.0
	v_lshlrev_b32_e32 v92, 16, v93
	v_and_b32_e32 v93, 0xffff0000, v93
	v_mul_f32_e32 v109, v108, v137
	v_pk_mul_f32 v[120:121], v[124:125], v[78:79] op_sel_hi:[0,1]
	v_pk_mul_f32 v[122:123], v[124:125], v[92:93] op_sel_hi:[0,1]
	v_pk_fma_f32 v[118:119], v[124:125], v[92:93], v[118:119] op_sel_hi:[0,1,1]
	v_fma_f32 v124, -v136, v109, v108
	v_fmac_f32_e32 v109, v124, v137
	v_fma_f32 v108, -v136, v109, v108
	v_readlane_b32 s2, v252, 0
	v_div_fmas_f32 v108, v108, v137, v109
	s_lshl_b32 s2, s2, 9
	v_div_fixup_f32 v108, v108, v125, 1.0
	s_add_i32 s2, s2, 0
	v_pk_fma_f32 v[122:123], v[108:109], v[118:119], v[122:123] op_sel_hi:[0,1,1] neg_lo:[0,0,1] neg_hi:[0,0,1]
	v_pk_fma_f32 v[108:109], v[108:109], v[126:127], v[120:121] op_sel_hi:[0,1,1] neg_lo:[0,0,1] neg_hi:[0,0,1]
	v_add3_u32 v120, s2, v162, v150
	v_cvt_pk_bf16_f32 v108, v108, v109
	v_cvt_pk_bf16_f32 v109, v122, v123
	ds_write_b64 v120, v[108:109]
	ds_read_b32 v120, v71 offset:120
	s_min_i32 s2, s92, -16
	s_add_i32 s2, s2, 24
	global_load_dwordx2 v[108:109], v[116:117], off
	ds_read_b32 v116, v71 offset:152
	s_waitcnt lgkmcnt(1)
	v_pk_fma_f32 v[118:119], v[120:121], v[130:131], v[118:119] op_sel_hi:[0,1,1] neg_lo:[1,0,0] neg_hi:[1,0,0]
	v_pk_fma_f32 v[120:121], v[120:121], v[106:107], v[126:127] op_sel_hi:[0,1,1] neg_lo:[1,0,0] neg_hi:[1,0,0]
	v_cvt_f32_i32_e32 v126, s2
	v_cndmask_b32_e64 v117, v91, 0, s[22:23]
	v_cndmask_b32_e64 v91, v90, 0, s[22:23]
	v_lshlrev_b32_e32 v90, 16, v91
	v_div_scale_f32 v127, s[2:3], v126, v126, 1.0
	v_rcp_f32_e32 v130, v127
	v_and_b32_e32 v91, 0xffff0000, v91
	v_lshlrev_b32_e32 v106, 16, v117
	v_and_b32_e32 v107, 0xffff0000, v117
	s_waitcnt lgkmcnt(0)
	v_pk_mul_f32 v[122:123], v[116:117], v[90:91] op_sel_hi:[0,1]
	v_pk_mul_f32 v[124:125], v[116:117], v[106:107] op_sel_hi:[0,1]
	v_pk_fma_f32 v[120:121], v[116:117], v[90:91], v[120:121] op_sel_hi:[0,1,1]
	v_pk_fma_f32 v[116:117], v[116:117], v[106:107], v[118:119] op_sel_hi:[0,1,1]
	v_fma_f32 v118, -v127, v130, 1.0
	v_fmac_f32_e32 v130, v118, v130
	v_div_scale_f32 v118, vcc, 1.0, v126, 1.0
	v_mul_f32_e32 v119, v118, v130
	v_fma_f32 v131, -v127, v119, v118
	v_fmac_f32_e32 v119, v131, v130
	v_fma_f32 v118, -v127, v119, v118
	v_readlane_b32 s2, v254, 62
	v_div_fmas_f32 v118, v118, v130, v119
	s_lshl_b32 s2, s2, 9
	v_div_fixup_f32 v118, v118, v126, 1.0
	s_add_i32 s2, s2, 0
	v_pk_fma_f32 v[124:125], v[118:119], v[116:117], v[124:125] op_sel_hi:[0,1,1] neg_lo:[0,0,1] neg_hi:[0,0,1]
	v_pk_fma_f32 v[118:119], v[118:119], v[120:121], v[122:123] op_sel_hi:[0,1,1] neg_lo:[0,0,1] neg_hi:[0,0,1]
	v_add3_u32 v122, s2, v160, v150
	s_min_i32 s2, s92, 0xffffffef
	s_add_i32 s2, s2, 25
	v_cvt_f32_i32_e32 v126, s2
	v_cvt_pk_bf16_f32 v118, v118, v119
	v_cvt_pk_bf16_f32 v119, v124, v125
	ds_write_b64 v122, v[118:119]
	ds_read_b32 v118, v71 offset:124
	v_cndmask_b32_e64 v119, v88, 0, s[20:21]
	ds_read_b32 v88, v71 offset:156
	v_div_scale_f32 v127, s[2:3], v126, v126, 1.0
	v_rcp_f32_e32 v130, v127
	s_waitcnt lgkmcnt(1)
	v_pk_fma_f32 v[116:117], v[118:119], v[134:135], v[116:117] op_sel_hi:[0,1,1] neg_lo:[1,0,0] neg_hi:[1,0,0]
	v_pk_fma_f32 v[104:105], v[118:119], v[104:105], v[120:121] op_sel_hi:[0,1,1] neg_lo:[1,0,0] neg_hi:[1,0,0]
	v_lshlrev_b32_e32 v118, 16, v119
	v_and_b32_e32 v119, 0xffff0000, v119
	v_lshlrev_b32_e32 v120, 16, v89
	v_and_b32_e32 v121, 0xffff0000, v89
	s_waitcnt lgkmcnt(0)
	v_pk_mul_f32 v[122:123], v[88:89], v[118:119] op_sel_hi:[0,1]
	v_pk_mul_f32 v[124:125], v[88:89], v[120:121] op_sel_hi:[0,1]
	v_pk_fma_f32 v[104:105], v[88:89], v[118:119], v[104:105] op_sel_hi:[0,1,1]
	v_pk_fma_f32 v[88:89], v[88:89], v[120:121], v[116:117] op_sel_hi:[0,1,1]
	v_fma_f32 v116, -v127, v130, 1.0
	v_fmac_f32_e32 v130, v116, v130
	v_div_scale_f32 v116, vcc, 1.0, v126, 1.0
	v_mul_f32_e32 v117, v116, v130
	v_fma_f32 v118, -v127, v117, v116
	v_fmac_f32_e32 v117, v118, v130
	v_fma_f32 v116, -v127, v117, v116
	v_div_fmas_f32 v116, v116, v130, v117
	v_readlane_b32 s2, v254, 60
	v_div_fixup_f32 v116, v116, v126, 1.0
	s_lshl_b32 s2, s2, 9
	v_pk_fma_f32 v[118:119], v[116:117], v[88:89], v[124:125] op_sel_hi:[0,1,1] neg_lo:[0,0,1] neg_hi:[0,0,1]
	v_pk_fma_f32 v[116:117], v[116:117], v[104:105], v[122:123] op_sel_hi:[0,1,1] neg_lo:[0,0,1] neg_hi:[0,0,1]
	s_add_i32 s2, s2, 0
	v_cvt_pk_bf16_f32 v116, v116, v117
	v_cvt_pk_bf16_f32 v117, v118, v119
	v_add3_u32 v118, s2, v155, v150
	s_min_i32 s2, s92, 0xffffffee
	s_add_i32 s2, s2, 26
	v_cvt_f32_i32_e32 v122, s2
	ds_write_b64 v118, v[116:117]
	ds_read_b32 v116, v71 offset:128
	v_cndmask_b32_e64 v117, v86, 0, s[18:19]
	ds_read_b32 v86, v71 offset:160
	v_div_scale_f32 v123, s[2:3], v122, v122, 1.0
	v_rcp_f32_e32 v124, v123
	s_waitcnt lgkmcnt(1)
	v_pk_fma_f32 v[88:89], v[116:117], v[132:133], v[88:89] op_sel_hi:[0,1,1] neg_lo:[1,0,0] neg_hi:[1,0,0]
	v_pk_fma_f32 v[102:103], v[116:117], v[102:103], v[104:105] op_sel_hi:[0,1,1] neg_lo:[1,0,0] neg_hi:[1,0,0]
	v_lshlrev_b32_e32 v104, 16, v117
	v_and_b32_e32 v105, 0xffff0000, v117
	v_lshlrev_b32_e32 v116, 16, v87
	v_and_b32_e32 v117, 0xffff0000, v87
	s_waitcnt lgkmcnt(0)
	v_pk_mul_f32 v[118:119], v[86:87], v[104:105] op_sel_hi:[0,1]
	v_pk_mul_f32 v[120:121], v[86:87], v[116:117] op_sel_hi:[0,1]
	v_pk_fma_f32 v[102:103], v[86:87], v[104:105], v[102:103] op_sel_hi:[0,1,1]
	v_pk_fma_f32 v[86:87], v[86:87], v[116:117], v[88:89] op_sel_hi:[0,1,1]
	v_fma_f32 v88, -v123, v124, 1.0
	v_fmac_f32_e32 v124, v88, v124
	v_div_scale_f32 v88, vcc, 1.0, v122, 1.0
	v_mul_f32_e32 v89, v88, v124
	v_fma_f32 v104, -v123, v89, v88
	v_fmac_f32_e32 v89, v104, v124
	v_fma_f32 v88, -v123, v89, v88
	v_div_fmas_f32 v88, v88, v124, v89
	v_readlane_b32 s2, v254, 58
	v_div_fixup_f32 v88, v88, v122, 1.0
	s_lshl_b32 s2, s2, 9
	v_pk_fma_f32 v[104:105], v[88:89], v[86:87], v[120:121] op_sel_hi:[0,1,1] neg_lo:[0,0,1] neg_hi:[0,0,1]
	v_pk_fma_f32 v[88:89], v[88:89], v[102:103], v[118:119] op_sel_hi:[0,1,1] neg_lo:[0,0,1] neg_hi:[0,0,1]
	s_add_i32 s2, s2, 0
	v_cvt_pk_bf16_f32 v88, v88, v89
	v_cvt_pk_bf16_f32 v89, v104, v105
	v_add3_u32 v104, s2, v151, v150
	s_min_i32 s2, s92, 0xffffffed
	s_add_i32 s2, s2, 27
	v_cvt_f32_i32_e32 v118, s2
	ds_write_b64 v104, v[88:89]
	ds_read_b32 v88, v71 offset:132
	v_cndmask_b32_e64 v104, v84, 0, s[16:17]
	ds_read_b32 v84, v71 offset:164
	v_div_scale_f32 v119, s[2:3], v118, v118, 1.0
	v_rcp_f32_e32 v120, v119
	s_waitcnt lgkmcnt(1)
	v_pk_fma_f32 v[86:87], v[88:89], v[128:129], v[86:87] op_sel_hi:[0,1,1] neg_lo:[1,0,0] neg_hi:[1,0,0]
	v_pk_fma_f32 v[88:89], v[88:89], v[100:101], v[102:103] op_sel_hi:[0,1,1] neg_lo:[1,0,0] neg_hi:[1,0,0]
	v_lshlrev_b32_e32 v100, 16, v104
	v_and_b32_e32 v101, 0xffff0000, v104
	v_lshlrev_b32_e32 v102, 16, v85
	v_and_b32_e32 v103, 0xffff0000, v85
	s_waitcnt lgkmcnt(0)
	v_pk_mul_f32 v[104:105], v[84:85], v[100:101] op_sel_hi:[0,1]
	v_pk_mul_f32 v[116:117], v[84:85], v[102:103] op_sel_hi:[0,1]
	v_pk_fma_f32 v[88:89], v[84:85], v[100:101], v[88:89] op_sel_hi:[0,1,1]
	v_pk_fma_f32 v[84:85], v[84:85], v[102:103], v[86:87] op_sel_hi:[0,1,1]
	v_fma_f32 v86, -v119, v120, 1.0
	v_fmac_f32_e32 v120, v86, v120
	v_div_scale_f32 v86, vcc, 1.0, v118, 1.0
	v_mul_f32_e32 v87, v86, v120
	v_fma_f32 v100, -v119, v87, v86
	v_fmac_f32_e32 v87, v100, v120
	v_fma_f32 v86, -v119, v87, v86
	v_div_fmas_f32 v86, v86, v120, v87
	v_readlane_b32 s2, v254, 56
	v_div_fixup_f32 v86, v86, v118, 1.0
	s_lshl_b32 s2, s2, 9
	v_pk_fma_f32 v[100:101], v[86:87], v[84:85], v[116:117] op_sel_hi:[0,1,1] neg_lo:[0,0,1] neg_hi:[0,0,1]
	v_pk_fma_f32 v[86:87], v[86:87], v[88:89], v[104:105] op_sel_hi:[0,1,1] neg_lo:[0,0,1] neg_hi:[0,0,1]
	s_add_i32 s2, s2, 0
	v_cvt_pk_bf16_f32 v86, v86, v87
	v_cvt_pk_bf16_f32 v87, v100, v101
	v_add3_u32 v100, s2, v144, v150
	s_min_i32 s2, s92, 0xffffffec
	ds_write_b64 v100, v[86:87]
	s_add_i32 s2, s2, 28
	v_cndmask_b32_e64 v73, v75, v73, s[10:11]
	v_cndmask_b32_e64 v72, v74, v72, s[10:11]
	ds_read_b32 v86, v71 offset:136
	v_cvt_f32_i32_e32 v105, s2
	global_load_dwordx2 v[72:73], v[72:73], off
	s_waitcnt vmcnt(1)
	v_cndmask_b32_e64 v104, v109, 0, s[8:9]
	v_cndmask_b32_e64 v100, v82, 0, s[14:15]
	ds_read_b32 v82, v71 offset:168
	v_div_scale_f32 v109, s[2:3], v105, v105, 1.0
	s_waitcnt lgkmcnt(1)
	v_pk_fma_f32 v[84:85], v[86:87], v[114:115], v[84:85] op_sel_hi:[0,1,1] neg_lo:[1,0,0] neg_hi:[1,0,0]
	v_rcp_f32_e32 v114, v109
	v_pk_fma_f32 v[86:87], v[86:87], v[98:99], v[88:89] op_sel_hi:[0,1,1] neg_lo:[1,0,0] neg_hi:[1,0,0]
	v_lshlrev_b32_e32 v88, 16, v100
	v_and_b32_e32 v89, 0xffff0000, v100
	v_lshlrev_b32_e32 v98, 16, v83
	v_and_b32_e32 v99, 0xffff0000, v83
	s_waitcnt lgkmcnt(0)
	v_pk_mul_f32 v[100:101], v[82:83], v[88:89] op_sel_hi:[0,1]
	v_pk_mul_f32 v[102:103], v[82:83], v[98:99] op_sel_hi:[0,1]
	v_pk_fma_f32 v[86:87], v[82:83], v[88:89], v[86:87] op_sel_hi:[0,1,1]
	v_pk_fma_f32 v[82:83], v[82:83], v[98:99], v[84:85] op_sel_hi:[0,1,1]
	v_fma_f32 v84, -v109, v114, 1.0
	v_fmac_f32_e32 v114, v84, v114
	v_div_scale_f32 v84, vcc, 1.0, v105, 1.0
	v_mul_f32_e32 v85, v84, v114
	v_fma_f32 v88, -v109, v85, v84
	v_fmac_f32_e32 v85, v88, v114
	v_fma_f32 v84, -v109, v85, v84
	v_div_fmas_f32 v84, v84, v114, v85
	v_readlane_b32 s2, v254, 54
	v_div_fixup_f32 v84, v84, v105, 1.0
	s_lshl_b32 s2, s2, 9
	v_pk_fma_f32 v[88:89], v[84:85], v[82:83], v[102:103] op_sel_hi:[0,1,1] neg_lo:[0,0,1] neg_hi:[0,0,1]
	v_pk_fma_f32 v[84:85], v[84:85], v[86:87], v[100:101] op_sel_hi:[0,1,1] neg_lo:[0,0,1] neg_hi:[0,0,1]
	s_add_i32 s2, s2, 0
	v_cvt_pk_bf16_f32 v84, v84, v85
	v_cvt_pk_bf16_f32 v85, v88, v89
	v_add3_u32 v88, s2, v145, v150
	s_min_i32 s2, s92, 0xffffffeb
	s_add_i32 s2, s2, 29
	v_cvt_f32_i32_e32 v75, s2
	ds_write_b64 v88, v[84:85]
	ds_read_b32 v84, v71 offset:140
	v_cndmask_b32_e64 v88, v80, 0, s[12:13]
	ds_read_b32 v80, v71 offset:172
	v_div_scale_f32 v100, s[2:3], v75, v75, 1.0
	v_rcp_f32_e32 v101, v100
	s_waitcnt lgkmcnt(1)
	v_pk_fma_f32 v[82:83], v[84:85], v[112:113], v[82:83] op_sel_hi:[0,1,1] neg_lo:[1,0,0] neg_hi:[1,0,0]
	v_pk_fma_f32 v[84:85], v[84:85], v[96:97], v[86:87] op_sel_hi:[0,1,1] neg_lo:[1,0,0] neg_hi:[1,0,0]
	v_lshlrev_b32_e32 v86, 16, v88
	v_and_b32_e32 v87, 0xffff0000, v88
	v_lshlrev_b32_e32 v88, 16, v81
	v_and_b32_e32 v89, 0xffff0000, v81
	s_waitcnt lgkmcnt(0)
	v_pk_mul_f32 v[96:97], v[80:81], v[86:87] op_sel_hi:[0,1]
	v_pk_mul_f32 v[98:99], v[80:81], v[88:89] op_sel_hi:[0,1]
	v_pk_fma_f32 v[84:85], v[80:81], v[86:87], v[84:85] op_sel_hi:[0,1,1]
	v_pk_fma_f32 v[80:81], v[80:81], v[88:89], v[82:83] op_sel_hi:[0,1,1]
	v_fma_f32 v82, -v100, v101, 1.0
	v_fmac_f32_e32 v101, v82, v101
	v_div_scale_f32 v82, vcc, 1.0, v75, 1.0
	v_mul_f32_e32 v83, v82, v101
	v_fma_f32 v86, -v100, v83, v82
	v_fmac_f32_e32 v83, v86, v101
	v_readlane_b32 s2, v254, 52
	v_fma_f32 v82, -v100, v83, v82
	s_lshl_b32 s2, s2, 9
	v_div_fmas_f32 v82, v82, v101, v83
	s_add_i32 s2, s2, 0
	v_div_fixup_f32 v82, v82, v75, 1.0
	v_add3_u32 v75, s2, v146, v150
	s_min_i32 s2, s92, 0xffffffea
	s_add_i32 s2, s2, 30
	v_pk_fma_f32 v[86:87], v[82:83], v[80:81], v[98:99] op_sel_hi:[0,1,1] neg_lo:[0,0,1] neg_hi:[0,0,1]
	v_pk_fma_f32 v[82:83], v[82:83], v[84:85], v[96:97] op_sel_hi:[0,1,1] neg_lo:[0,0,1] neg_hi:[0,0,1]
	v_cvt_f32_i32_e32 v96, s2
	v_cvt_pk_bf16_f32 v82, v82, v83
	v_cvt_pk_bf16_f32 v83, v86, v87
	ds_write_b64 v75, v[82:83]
	ds_read_b32 v82, v71 offset:144
	ds_read_b32 v74, v71 offset:176
	v_div_scale_f32 v97, s[2:3], v96, v96, 1.0
	v_rcp_f32_e32 v98, v97
	v_cndmask_b32_e64 v75, v108, 0, s[8:9]
	s_waitcnt lgkmcnt(1)
	v_pk_fma_f32 v[80:81], v[82:83], v[110:111], v[80:81] op_sel_hi:[0,1,1] neg_lo:[1,0,0] neg_hi:[1,0,0]
	v_pk_fma_f32 v[82:83], v[82:83], v[94:95], v[84:85] op_sel_hi:[0,1,1] neg_lo:[1,0,0] neg_hi:[1,0,0]
	v_lshlrev_b32_e32 v84, 16, v75
	v_and_b32_e32 v85, 0xffff0000, v75
	v_lshlrev_b32_e32 v86, 16, v104
	v_and_b32_e32 v87, 0xffff0000, v104
	s_waitcnt lgkmcnt(0)
	v_pk_mul_f32 v[88:89], v[74:75], v[84:85] op_sel_hi:[0,1]
	v_pk_mul_f32 v[94:95], v[74:75], v[86:87] op_sel_hi:[0,1]
	v_pk_fma_f32 v[82:83], v[74:75], v[84:85], v[82:83] op_sel_hi:[0,1,1]
	v_pk_fma_f32 v[74:75], v[74:75], v[86:87], v[80:81] op_sel_hi:[0,1,1]
	v_fma_f32 v80, -v97, v98, 1.0
	v_fmac_f32_e32 v98, v80, v98
	v_div_scale_f32 v80, vcc, 1.0, v96, 1.0
	v_mul_f32_e32 v81, v80, v98
	v_fma_f32 v84, -v97, v81, v80
	v_fmac_f32_e32 v81, v84, v98
	v_fma_f32 v80, -v97, v81, v80
	v_div_fmas_f32 v80, v80, v98, v81
	v_readlane_b32 s2, v254, 50
	v_div_fixup_f32 v80, v80, v96, 1.0
	s_lshl_b32 s2, s2, 9
	v_pk_fma_f32 v[84:85], v[80:81], v[74:75], v[94:95] op_sel_hi:[0,1,1] neg_lo:[0,0,1] neg_hi:[0,0,1]
	v_pk_fma_f32 v[80:81], v[80:81], v[82:83], v[88:89] op_sel_hi:[0,1,1] neg_lo:[0,0,1] neg_hi:[0,0,1]
	s_add_i32 s2, s2, 0
	v_cvt_pk_bf16_f32 v80, v80, v81
	v_cvt_pk_bf16_f32 v81, v84, v85
	v_add3_u32 v84, s2, v142, v150
	ds_write_b64 v84, v[80:81]
	ds_read_b32 v80, v71 offset:148
	s_min_i32 s2, s92, 0xffffffe9
	v_cndmask_b32_e64 v81, v76, 0, s[6:7]
	ds_read_b32 v76, v71 offset:180
	s_add_i32 s2, s2, 31
	v_cvt_f32_i32_e32 v88, s2
	s_waitcnt lgkmcnt(1)
	v_pk_fma_f32 v[74:75], v[80:81], v[92:93], v[74:75] op_sel_hi:[0,1,1] neg_lo:[1,0,0] neg_hi:[1,0,0]
	v_pk_fma_f32 v[78:79], v[80:81], v[78:79], v[82:83] op_sel_hi:[0,1,1] neg_lo:[1,0,0] neg_hi:[1,0,0]
	v_lshlrev_b32_e32 v80, 16, v81
	v_and_b32_e32 v81, 0xffff0000, v81
	v_lshlrev_b32_e32 v82, 16, v77
	v_and_b32_e32 v83, 0xffff0000, v77
	s_waitcnt lgkmcnt(0)
	v_pk_mul_f32 v[84:85], v[76:77], v[80:81] op_sel_hi:[0,1]
	v_div_scale_f32 v77, s[2:3], v88, v88, 1.0
	v_rcp_f32_e32 v89, v77
	v_pk_mul_f32 v[86:87], v[76:77], v[82:83] op_sel_hi:[0,1]
	v_pk_fma_f32 v[78:79], v[76:77], v[80:81], v[78:79] op_sel_hi:[0,1,1]
	v_pk_fma_f32 v[74:75], v[76:77], v[82:83], v[74:75] op_sel_hi:[0,1,1]
	v_fma_f32 v76, -v77, v89, 1.0
	v_fmac_f32_e32 v89, v76, v89
	v_div_scale_f32 v76, vcc, 1.0, v88, 1.0
	v_mul_f32_e32 v80, v76, v89
	v_fma_f32 v81, -v77, v80, v76
	v_fmac_f32_e32 v80, v81, v89
	v_fma_f32 v76, -v77, v80, v76
	v_div_fmas_f32 v76, v76, v89, v80
	v_readlane_b32 s2, v254, 49
	v_div_fixup_f32 v76, v76, v88, 1.0
	s_lshl_b32 s2, s2, 9
	v_pk_fma_f32 v[80:81], v[76:77], v[74:75], v[86:87] op_sel_hi:[0,1,1] neg_lo:[0,0,1] neg_hi:[0,0,1]
	v_pk_fma_f32 v[76:77], v[76:77], v[78:79], v[84:85] op_sel_hi:[0,1,1] neg_lo:[0,0,1] neg_hi:[0,0,1]
	s_add_i32 s2, s2, 0
	v_cvt_pk_bf16_f32 v76, v76, v77
	v_cvt_pk_bf16_f32 v77, v80, v81
	v_add3_u32 v80, s2, v140, v150
	s_min_i32 s2, s92, 0xffffffe8
	ds_write_b64 v80, v[76:77]
	s_add_i32 s2, s2, 32
	ds_read_b32 v76, v71 offset:152
	s_waitcnt vmcnt(0)
	v_cndmask_b32_e64 v80, v72, 0, s[10:11]
	ds_read_b32 v72, v71 offset:184
	v_cvt_f32_i32_e32 v71, s2
	v_cndmask_b32_e64 v73, v73, 0, s[10:11]
	s_waitcnt lgkmcnt(1)
	v_pk_fma_f32 v[74:75], v[76:77], v[106:107], v[74:75] op_sel_hi:[0,1,1] neg_lo:[1,0,0] neg_hi:[1,0,0]
	v_pk_fma_f32 v[76:77], v[76:77], v[90:91], v[78:79] op_sel_hi:[0,1,1] neg_lo:[1,0,0] neg_hi:[1,0,0]
	v_div_scale_f32 v86, s[2:3], v71, v71, 1.0
	v_rcp_f32_e32 v87, v86
	v_lshlrev_b32_e32 v78, 16, v80
	v_and_b32_e32 v79, 0xffff0000, v80
	v_lshlrev_b32_e32 v80, 16, v73
	v_and_b32_e32 v81, 0xffff0000, v73
	s_waitcnt lgkmcnt(0)
	v_pk_mul_f32 v[82:83], v[72:73], v[78:79] op_sel_hi:[0,1]
	v_pk_mul_f32 v[84:85], v[72:73], v[80:81] op_sel_hi:[0,1]
	v_pk_fma_f32 v[76:77], v[72:73], v[78:79], v[76:77] op_sel_hi:[0,1,1]
	v_pk_fma_f32 v[72:73], v[72:73], v[80:81], v[74:75] op_sel_hi:[0,1,1]
	v_fma_f32 v74, -v86, v87, 1.0
	v_fmac_f32_e32 v87, v74, v87
	v_div_scale_f32 v74, vcc, 1.0, v71, 1.0
	v_mul_f32_e32 v75, v74, v87
	v_fma_f32 v78, -v86, v75, v74
	v_fmac_f32_e32 v75, v78, v87
	v_fma_f32 v74, -v86, v75, v74
	v_div_fmas_f32 v74, v74, v87, v75
	v_div_fixup_f32 v74, v74, v71, 1.0
	v_readlane_b32 s38, v252, 7
	v_pk_fma_f32 v[78:79], v[74:75], v[72:73], v[84:85] op_sel_hi:[0,1,1] neg_lo:[0,0,1] neg_hi:[0,0,1]
	v_pk_fma_f32 v[72:73], v[74:75], v[76:77], v[82:83] op_sel_hi:[0,1,1] neg_lo:[0,0,1] neg_hi:[0,0,1]
	v_readlane_b32 s2, v254, 48
	v_readlane_b32 s6, v254, 6
	v_readlane_b32 s42, v254, 20
	v_readlane_b32 s50, v254, 31
	v_readlane_b32 s39, v252, 8
	s_mov_b32 s18, s86
	s_mov_b32 s16, s92
	v_cvt_pk_bf16_f32 v72, v72, v73
	v_cvt_pk_bf16_f32 v73, v78, v79
	v_mov_b32_e32 v74, s2
	v_readlane_b32 s7, v254, 7
	v_readlane_b32 s92, v254, 9
	v_readlane_b32 s95, v254, 12
	v_readlane_b32 s43, v254, 21
	v_readlane_b32 s41, v254, 25
	s_mov_b32 s44, 0xf800000
	s_movk_i32 s12, 0x1ff
	v_readlane_b32 s46, v254, 30
	v_readlane_b32 s51, v254, 32
	v_readlane_b32 s15, v254, 46
	s_mov_b64 s[8:9], 0
